# GEMM epilogues P3/P5/P10: residual/statistic loads hoisted to epilogue top, row-sum atomics issued together at the end
# speedup vs baseline: 1.0227x; 1.0012x over previous
.LBB0_594:
	v_lshl_or_b32 v166, s48, 8, v178
	v_lshl_add_u32 v152, s8, 8, v176
	v_ashrrev_i32_e32 v167, 31, v166
	v_ashrrev_i32_e32 v153, 31, v152
	v_lshl_add_u64 v[160:161], v[166:167], 2, s[14:15]
	v_lshl_add_u64 v[154:155], v[152:153], 2, s[22:23]
	global_load_dwordx4 v[156:159], v[160:161], off
	global_load_dwordx4 v[168:171], v[160:161], off offset:16
	s_nop 0
	v_lshlrev_b64 v[162:163], 10, v[152:153]
	v_lshl_add_u64 v[164:165], v[162:163], 0, v[166:167]
	v_lshlrev_b64 v[162:163], 1, v[164:165]
	v_lshl_add_u64 v[192:193], s[18:19], 0, v[162:163]
	s_nop 0
	global_load_dwordx4 v[184:187], v[160:161], off offset:528
	global_load_dwordx4 v[188:191], v[160:161], off offset:512
	v_mov_b64_e32 v[198:199], v[192:193]
	s_mov_b32 s99, 0
	global_load_dword v202, v[154:155], off
	global_load_dword v203, v[154:155], off offset:64
	global_load_dword v204, v[154:155], off offset:128
	global_load_dword v205, v[154:155], off offset:192
	global_load_dword v206, v[154:155], off offset:512
	global_load_dword v207, v[154:155], off offset:576
	global_load_dword v212, v[154:155], off offset:640
	global_load_dword v213, v[154:155], off offset:704
	global_load_dwordx4 v[216:219], v[198:199], off
	global_load_dwordx4 v[220:223], v[198:199], off offset:256
	s_mov_b32 s98, 0x8000
	v_lshl_add_u64 v[200:201], v[198:199], 0, s[98:99]
	global_load_dwordx4 v[224:227], v[200:201], off
	s_mov_b32 s98, 0x8000
	v_lshl_add_u64 v[200:201], v[198:199], 0, s[98:99]
	global_load_dwordx4 v[228:231], v[200:201], off offset:256
	s_mov_b32 s98, 0x10000
	v_lshl_add_u64 v[200:201], v[198:199], 0, s[98:99]
	global_load_dwordx4 v[232:235], v[200:201], off
	s_mov_b32 s98, 0x10000
	v_lshl_add_u64 v[200:201], v[198:199], 0, s[98:99]
	global_load_dwordx4 v[236:239], v[200:201], off offset:256
	s_mov_b32 s98, 0x18000
	v_lshl_add_u64 v[200:201], v[198:199], 0, s[98:99]
	global_load_dwordx4 v[240:243], v[200:201], off
	v_lshl_add_u64 v[196:197], s[20:21], 0, v[162:163]
	s_andn2_b64 vcc, exec, s[38:39]
	s_waitcnt vmcnt(6)
	v_mov_b32_e32 v183, v202
	v_mov_b64_e32 v[172:173], v[216:217]
	v_mov_b64_e32 v[174:175], v[218:219]
	s_mov_b32 s98, 0x18000
	v_lshl_add_u64 v[200:201], v[198:199], 0, s[98:99]
	global_load_dwordx4 v[216:219], v[200:201], off offset:256
	v_rcp_f32_e32 v160, v158
	v_rcp_f32_e32 v158, v168
	v_fmamk_f32 v168, v183, 0x3a800000, v182
	v_sqrt_f32_e32 v168, v168
	v_rcp_f32_e32 v156, v156
	v_rcp_f32_e32 v157, v157
	v_rcp_f32_e32 v161, v159
	v_rcp_f32_e32 v159, v169
	v_rcp_f32_e32 v162, v170
	v_rcp_f32_e32 v163, v171
	v_lshlrev_b32_e32 v170, 16, v172
	v_and_b32_e32 v171, 0xffff0000, v172
	v_lshlrev_b32_e32 v172, 16, v173
	v_and_b32_e32 v173, 0xffff0000, v173
	v_lshlrev_b32_e32 v194, 16, v174
	v_and_b32_e32 v195, 0xffff0000, v174
	v_lshlrev_b32_e32 v174, 16, v175
	v_and_b32_e32 v175, 0xffff0000, v175
	v_pk_mul_f32 v[170:171], v[168:169], v[170:171] op_sel_hi:[0,1]
	v_pk_mul_f32 v[172:173], v[168:169], v[172:173] op_sel_hi:[0,1]
	v_pk_mul_f32 v[194:195], v[168:169], v[194:195] op_sel_hi:[0,1]
	v_pk_mul_f32 v[174:175], v[168:169], v[174:175] op_sel_hi:[0,1]
	v_pk_fma_f32 v[168:169], v[160:161], v[172:173], v[126:127]
	v_pk_fma_f32 v[170:171], v[156:157], v[170:171], v[124:125]
	v_pk_fma_f32 v[172:173], v[162:163], v[174:175], v[122:123]
	v_pk_fma_f32 v[174:175], v[158:159], v[194:195], v[120:121]
	v_cvt_pk_bf16_f32 v120, v170, v171
	v_cvt_pk_bf16_f32 v121, v168, v169
	v_rcp_f32_e32 v126, v190
	v_cvt_pk_bf16_f32 v122, v174, v175
	v_cvt_pk_bf16_f32 v123, v172, v173
	global_store_dwordx4 v[196:197], v[120:123], off
	s_nop 0
	s_nop 0
	s_nop 0
	v_cndmask_b32_e64 v120, 0, 1, s[38:39]
	v_cmp_ne_u32_e64 s[8:9], 1, v120
	v_rcp_f32_e32 v122, v188
	v_rcp_f32_e32 v123, v189
	v_rcp_f32_e32 v127, v191
	v_rcp_f32_e32 v120, v184
	v_rcp_f32_e32 v121, v185
	v_rcp_f32_e32 v124, v186
	v_rcp_f32_e32 v125, v187
	s_waitcnt vmcnt(6)
	v_mov_b64_e32 v[192:193], v[220:221]
	v_mov_b64_e32 v[194:195], v[222:223]
	s_mov_b32 s98, 0x40000
	v_lshl_add_u64 v[200:201], v[198:199], 0, s[98:99]
	global_load_dwordx4 v[220:223], v[200:201], off
	v_lshlrev_b32_e32 v184, 16, v192
	v_mov_b32_e32 v183, v202
	v_fmamk_f32 v183, v183, 0x3a800000, v182
	v_sqrt_f32_e32 v190, v183
	v_and_b32_e32 v185, 0xffff0000, v192
	v_lshlrev_b32_e32 v186, 16, v193
	v_and_b32_e32 v187, 0xffff0000, v193
	v_lshlrev_b32_e32 v188, 16, v194
	v_and_b32_e32 v189, 0xffff0000, v194
	v_lshlrev_b32_e32 v192, 16, v195
	v_and_b32_e32 v193, 0xffff0000, v195
	v_pk_mul_f32 v[184:185], v[190:191], v[184:185] op_sel_hi:[0,1]
	v_pk_mul_f32 v[186:187], v[190:191], v[186:187] op_sel_hi:[0,1]
	v_pk_mul_f32 v[188:189], v[190:191], v[188:189] op_sel_hi:[0,1]
	v_pk_mul_f32 v[190:191], v[190:191], v[192:193] op_sel_hi:[0,1]
	v_pk_fma_f32 v[118:119], v[126:127], v[186:187], v[118:119]
	v_pk_fma_f32 v[116:117], v[122:123], v[184:185], v[116:117]
	v_pk_fma_f32 v[114:115], v[124:125], v[190:191], v[114:115]
	v_pk_fma_f32 v[112:113], v[120:121], v[188:189], v[112:113]
	v_cvt_pk_bf16_f32 v184, v116, v117
	v_cvt_pk_bf16_f32 v185, v118, v119
	s_nop 0
	v_cvt_pk_bf16_f32 v186, v112, v113
	v_cvt_pk_bf16_f32 v187, v114, v115
	global_store_dwordx4 v[196:197], v[184:187], off offset:256
	s_cbranch_vccnz .LBB0_598
	v_mul_f32_e32 v174, v174, v174
	v_mul_f32_e32 v170, v170, v170
	v_mul_f32_e32 v116, v116, v116
	v_mul_f32_e32 v112, v112, v112
	v_fmac_f32_e32 v174, v175, v175
	v_fmac_f32_e32 v170, v171, v171
	v_fmac_f32_e32 v116, v117, v117
	v_fmac_f32_e32 v112, v113, v113
	v_fmac_f32_e32 v174, v172, v172
	v_fmac_f32_e32 v170, v168, v168
	v_fmac_f32_e32 v116, v118, v118
	v_fmac_f32_e32 v112, v114, v114
	v_fmac_f32_e32 v174, v173, v173
	v_fmac_f32_e32 v170, v169, v169
	v_fmac_f32_e32 v116, v119, v119
	v_fmac_f32_e32 v112, v115, v115
	v_add_f32_e32 v168, v174, v170
	v_add_f32_e32 v112, v112, v116
	v_add_f32_e32 v112, v168, v112
	v_mov_b32_e32 v113, v112
	s_nop 1
	v_permlane16_swap_b32_e32 v112, v113
	v_add_f32_e32 v112, v112, v113
	v_mov_b32_e32 v113, v112
	s_nop 1
	v_permlane32_swap_b32_e32 v112, v113
	s_and_saveexec_b64 s[48:49], s[4:5]
	s_cbranch_execz .LBB0_597
	v_lshl_add_u64 v[114:115], v[152:153], 2, s[12:13]
	v_mov_b64_e32 v[244:245], v[114:115]
	v_add_f32_e32 v112, v112, v113
	v_mov_b32_e32 v214, v112

.LBB0_598:
	v_or_b32_e32 v112, 16, v152
	v_ashrrev_i32_e32 v113, 31, v112
	v_lshl_add_u64 v[118:119], v[112:113], 2, s[22:23]
	v_lshlrev_b64 v[114:115], 10, v[112:113]
	s_nop 0
	v_lshl_add_u64 v[114:115], v[114:115], 0, v[166:167]
	v_lshlrev_b64 v[116:117], 1, v[114:115]
	v_lshl_add_u64 v[168:169], s[18:19], 0, v[116:117]
	s_nop 0
	v_lshl_add_u64 v[116:117], s[20:21], 0, v[116:117]
	s_and_b64 vcc, exec, s[8:9]
	v_mov_b32_e32 v170, v203
	v_fmamk_f32 v170, v170, 0x3a800000, v182
	v_sqrt_f32_e32 v170, v170
	s_waitcnt vmcnt(6)
	v_mov_b64_e32 v[112:113], v[224:225]
	v_mov_b64_e32 v[114:115], v[226:227]
	s_mov_b32 s98, 0x40000
	v_lshl_add_u64 v[200:201], v[198:199], 0, s[98:99]
	global_load_dwordx4 v[224:227], v[200:201], off offset:256
	v_lshlrev_b32_e32 v172, 16, v112
	v_and_b32_e32 v173, 0xffff0000, v112
	v_lshlrev_b32_e32 v112, 16, v113
	v_and_b32_e32 v113, 0xffff0000, v113
	v_lshlrev_b32_e32 v174, 16, v114
	v_and_b32_e32 v175, 0xffff0000, v114
	v_lshlrev_b32_e32 v114, 16, v115
	v_and_b32_e32 v115, 0xffff0000, v115
	v_pk_mul_f32 v[172:173], v[170:171], v[172:173] op_sel_hi:[0,1]
	v_pk_mul_f32 v[112:113], v[170:171], v[112:113] op_sel_hi:[0,1]
	v_pk_mul_f32 v[174:175], v[170:171], v[174:175] op_sel_hi:[0,1]
	v_pk_mul_f32 v[114:115], v[170:171], v[114:115] op_sel_hi:[0,1]
	v_pk_fma_f32 v[110:111], v[160:161], v[112:113], v[110:111]
	v_pk_fma_f32 v[108:109], v[156:157], v[172:173], v[108:109]
	v_pk_fma_f32 v[106:107], v[162:163], v[114:115], v[106:107]
	v_pk_fma_f32 v[104:105], v[158:159], v[174:175], v[104:105]
	v_cvt_pk_bf16_f32 v112, v108, v109
	v_cvt_pk_bf16_f32 v113, v110, v111
	s_nop 0
	v_cvt_pk_bf16_f32 v114, v104, v105
	v_cvt_pk_bf16_f32 v115, v106, v107
	global_store_dwordx4 v[116:117], v[112:115], off
	s_nop 0
	s_nop 0
	s_nop 0
	s_waitcnt vmcnt(6)
	v_mov_b64_e32 v[112:113], v[228:229]
	v_mov_b64_e32 v[114:115], v[230:231]
	s_mov_b32 s98, 0x48000
	v_lshl_add_u64 v[200:201], v[198:199], 0, s[98:99]
	global_load_dwordx4 v[228:231], v[200:201], off
	v_lshlrev_b32_e32 v118, 16, v112
	v_mov_b32_e32 v169, v203
	v_fmamk_f32 v169, v169, 0x3a800000, v182
	v_sqrt_f32_e32 v170, v169
	v_and_b32_e32 v119, 0xffff0000, v112
	v_lshlrev_b32_e32 v112, 16, v113
	v_and_b32_e32 v113, 0xffff0000, v113
	v_lshlrev_b32_e32 v168, 16, v114
	v_and_b32_e32 v169, 0xffff0000, v114
	v_lshlrev_b32_e32 v114, 16, v115
	v_and_b32_e32 v115, 0xffff0000, v115
	v_pk_mul_f32 v[118:119], v[170:171], v[118:119] op_sel_hi:[0,1]
	v_pk_mul_f32 v[112:113], v[170:171], v[112:113] op_sel_hi:[0,1]
	v_pk_mul_f32 v[168:169], v[170:171], v[168:169] op_sel_hi:[0,1]
	v_pk_mul_f32 v[114:115], v[170:171], v[114:115] op_sel_hi:[0,1]
	v_pk_fma_f32 v[102:103], v[126:127], v[112:113], v[102:103]
	v_pk_fma_f32 v[100:101], v[122:123], v[118:119], v[100:101]
	v_pk_fma_f32 v[98:99], v[124:125], v[114:115], v[98:99]
	v_pk_fma_f32 v[96:97], v[120:121], v[168:169], v[96:97]
	v_cvt_pk_bf16_f32 v112, v100, v101
	v_cvt_pk_bf16_f32 v113, v102, v103
	s_nop 0
	v_cvt_pk_bf16_f32 v114, v96, v97
	v_cvt_pk_bf16_f32 v115, v98, v99
	global_store_dwordx4 v[116:117], v[112:115], off offset:256
	s_cbranch_vccnz .LBB0_602
	v_mul_f32_e32 v104, v104, v104
	v_fmac_f32_e32 v104, v105, v105
	v_mul_f32_e32 v105, v108, v108
	v_mul_f32_e32 v100, v100, v100
	v_mul_f32_e32 v96, v96, v96
	v_fmac_f32_e32 v105, v109, v109
	v_fmac_f32_e32 v100, v101, v101
	v_fmac_f32_e32 v96, v97, v97
	v_fmac_f32_e32 v104, v106, v106
	v_fmac_f32_e32 v105, v110, v110
	v_fmac_f32_e32 v100, v102, v102
	v_fmac_f32_e32 v96, v98, v98
	v_fmac_f32_e32 v104, v107, v107
	v_fmac_f32_e32 v105, v111, v111
	v_fmac_f32_e32 v100, v103, v103
	v_fmac_f32_e32 v96, v99, v99
	v_add_f32_e32 v104, v104, v105
	v_add_f32_e32 v96, v96, v100
	v_add_f32_e32 v96, v104, v96
	v_mov_b32_e32 v97, v96
	s_nop 1
	v_permlane16_swap_b32_e32 v96, v97
	v_add_f32_e32 v96, v96, v97
	v_mov_b32_e32 v97, v96
	s_nop 1
	v_permlane32_swap_b32_e32 v96, v97
	s_and_saveexec_b64 s[48:49], s[4:5]
	s_cbranch_execz .LBB0_601
	v_lshl_add_u64 v[98:99], v[152:153], 2, s[12:13]
	v_add_f32_e32 v96, v96, v97
	v_mov_b32_e32 v215, v96

.LBB0_602:
	v_or_b32_e32 v96, 32, v152
	v_ashrrev_i32_e32 v97, 31, v96
	v_lshl_add_u64 v[102:103], v[96:97], 2, s[22:23]
	v_lshlrev_b64 v[98:99], 10, v[96:97]
	s_nop 0
	v_lshl_add_u64 v[98:99], v[98:99], 0, v[166:167]
	v_lshlrev_b64 v[100:101], 1, v[98:99]
	v_lshl_add_u64 v[104:105], s[18:19], 0, v[100:101]
	s_nop 0
	v_lshl_add_u64 v[100:101], s[20:21], 0, v[100:101]
	s_and_b64 vcc, exec, s[8:9]
	v_mov_b32_e32 v106, v204
	v_fmamk_f32 v106, v106, 0x3a800000, v182
	v_sqrt_f32_e32 v106, v106
	s_waitcnt vmcnt(6)
	v_mov_b64_e32 v[96:97], v[232:233]
	v_mov_b64_e32 v[98:99], v[234:235]
	s_mov_b32 s98, 0x48000
	v_lshl_add_u64 v[200:201], v[198:199], 0, s[98:99]
	global_load_dwordx4 v[232:235], v[200:201], off offset:256
	v_lshlrev_b32_e32 v108, 16, v96
	v_and_b32_e32 v109, 0xffff0000, v96
	v_lshlrev_b32_e32 v96, 16, v97
	v_and_b32_e32 v97, 0xffff0000, v97
	v_lshlrev_b32_e32 v110, 16, v98
	v_and_b32_e32 v111, 0xffff0000, v98
	v_lshlrev_b32_e32 v98, 16, v99
	v_and_b32_e32 v99, 0xffff0000, v99
	v_pk_mul_f32 v[108:109], v[106:107], v[108:109] op_sel_hi:[0,1]
	v_pk_mul_f32 v[96:97], v[106:107], v[96:97] op_sel_hi:[0,1]
	v_pk_mul_f32 v[110:111], v[106:107], v[110:111] op_sel_hi:[0,1]
	v_pk_mul_f32 v[98:99], v[106:107], v[98:99] op_sel_hi:[0,1]
	v_pk_fma_f32 v[94:95], v[160:161], v[96:97], v[94:95]
	v_pk_fma_f32 v[92:93], v[156:157], v[108:109], v[92:93]
	v_pk_fma_f32 v[90:91], v[162:163], v[98:99], v[90:91]
	v_pk_fma_f32 v[88:89], v[158:159], v[110:111], v[88:89]
	v_cvt_pk_bf16_f32 v96, v92, v93
	v_cvt_pk_bf16_f32 v97, v94, v95
	s_nop 0
	v_cvt_pk_bf16_f32 v98, v88, v89
	v_cvt_pk_bf16_f32 v99, v90, v91
	global_store_dwordx4 v[100:101], v[96:99], off
	s_nop 0
	s_nop 0
	s_nop 0
	s_waitcnt vmcnt(6)
	v_mov_b64_e32 v[96:97], v[236:237]
	v_mov_b64_e32 v[98:99], v[238:239]
	s_mov_b32 s98, 0x50000
	v_lshl_add_u64 v[200:201], v[198:199], 0, s[98:99]
	global_load_dwordx4 v[236:239], v[200:201], off
	v_lshlrev_b32_e32 v102, 16, v96
	v_mov_b32_e32 v105, v204
	v_fmamk_f32 v105, v105, 0x3a800000, v182
	v_sqrt_f32_e32 v106, v105
	v_and_b32_e32 v103, 0xffff0000, v96
	v_lshlrev_b32_e32 v96, 16, v97
	v_and_b32_e32 v97, 0xffff0000, v97
	v_lshlrev_b32_e32 v104, 16, v98
	v_and_b32_e32 v105, 0xffff0000, v98
	v_lshlrev_b32_e32 v98, 16, v99
	v_and_b32_e32 v99, 0xffff0000, v99
	v_pk_mul_f32 v[102:103], v[106:107], v[102:103] op_sel_hi:[0,1]
	v_pk_mul_f32 v[96:97], v[106:107], v[96:97] op_sel_hi:[0,1]
	v_pk_mul_f32 v[104:105], v[106:107], v[104:105] op_sel_hi:[0,1]
	v_pk_mul_f32 v[98:99], v[106:107], v[98:99] op_sel_hi:[0,1]
	v_pk_fma_f32 v[86:87], v[126:127], v[96:97], v[86:87]
	v_pk_fma_f32 v[84:85], v[122:123], v[102:103], v[84:85]
	v_pk_fma_f32 v[82:83], v[124:125], v[98:99], v[82:83]
	v_pk_fma_f32 v[80:81], v[120:121], v[104:105], v[80:81]
	v_cvt_pk_bf16_f32 v96, v84, v85
	v_cvt_pk_bf16_f32 v97, v86, v87
	s_nop 0
	v_cvt_pk_bf16_f32 v98, v80, v81
	v_cvt_pk_bf16_f32 v99, v82, v83
	global_store_dwordx4 v[100:101], v[96:99], off offset:256
	s_cbranch_vccnz .LBB0_606
	v_mul_f32_e32 v88, v88, v88
	v_fmac_f32_e32 v88, v89, v89
	v_mul_f32_e32 v89, v92, v92
	v_mul_f32_e32 v84, v84, v84
	v_mul_f32_e32 v80, v80, v80
	v_fmac_f32_e32 v89, v93, v93
	v_fmac_f32_e32 v84, v85, v85
	v_fmac_f32_e32 v80, v81, v81
	v_fmac_f32_e32 v88, v90, v90
	v_fmac_f32_e32 v89, v94, v94
	v_fmac_f32_e32 v84, v86, v86
	v_fmac_f32_e32 v80, v82, v82
	v_fmac_f32_e32 v88, v91, v91
	v_fmac_f32_e32 v89, v95, v95
	v_fmac_f32_e32 v84, v87, v87
	v_fmac_f32_e32 v80, v83, v83
	v_add_f32_e32 v88, v88, v89
	v_add_f32_e32 v80, v80, v84
	v_add_f32_e32 v80, v88, v80
	v_mov_b32_e32 v81, v80
	s_nop 1
	v_permlane16_swap_b32_e32 v80, v81
	v_add_f32_e32 v80, v80, v81
	v_mov_b32_e32 v81, v80
	s_nop 1
	v_permlane32_swap_b32_e32 v80, v81
	s_and_saveexec_b64 s[48:49], s[4:5]
	s_cbranch_execz .LBB0_605
	v_lshl_add_u64 v[82:83], v[152:153], 2, s[12:13]
	v_add_f32_e32 v80, v80, v81
	v_mov_b32_e32 v248, v80

.LBB0_606:
	v_or_b32_e32 v80, 48, v152
	v_ashrrev_i32_e32 v81, 31, v80
	v_lshl_add_u64 v[86:87], v[80:81], 2, s[22:23]
	v_lshlrev_b64 v[82:83], 10, v[80:81]
	s_nop 0
	v_lshl_add_u64 v[82:83], v[82:83], 0, v[166:167]
	v_lshlrev_b64 v[84:85], 1, v[82:83]
	v_lshl_add_u64 v[88:89], s[18:19], 0, v[84:85]
	s_nop 0
	v_lshl_add_u64 v[84:85], s[20:21], 0, v[84:85]
	s_and_b64 vcc, exec, s[8:9]
	v_mov_b32_e32 v90, v205
	v_fmamk_f32 v90, v90, 0x3a800000, v182
	v_sqrt_f32_e32 v90, v90
	s_waitcnt vmcnt(6)
	v_mov_b64_e32 v[80:81], v[240:241]
	v_mov_b64_e32 v[82:83], v[242:243]
	s_mov_b32 s98, 0x50000
	v_lshl_add_u64 v[200:201], v[198:199], 0, s[98:99]
	global_load_dwordx4 v[240:243], v[200:201], off offset:256
	v_lshlrev_b32_e32 v92, 16, v80
	v_and_b32_e32 v93, 0xffff0000, v80
	v_lshlrev_b32_e32 v80, 16, v81
	v_and_b32_e32 v81, 0xffff0000, v81
	v_lshlrev_b32_e32 v94, 16, v82
	v_and_b32_e32 v95, 0xffff0000, v82
	v_lshlrev_b32_e32 v82, 16, v83
	v_and_b32_e32 v83, 0xffff0000, v83
	v_pk_mul_f32 v[92:93], v[90:91], v[92:93] op_sel_hi:[0,1]
	v_pk_mul_f32 v[80:81], v[90:91], v[80:81] op_sel_hi:[0,1]
	v_pk_mul_f32 v[94:95], v[90:91], v[94:95] op_sel_hi:[0,1]
	v_pk_mul_f32 v[82:83], v[90:91], v[82:83] op_sel_hi:[0,1]
	v_pk_fma_f32 v[78:79], v[160:161], v[80:81], v[78:79]
	v_pk_fma_f32 v[76:77], v[156:157], v[92:93], v[76:77]
	v_pk_fma_f32 v[74:75], v[162:163], v[82:83], v[74:75]
	v_pk_fma_f32 v[72:73], v[158:159], v[94:95], v[72:73]
	v_cvt_pk_bf16_f32 v80, v76, v77
	v_cvt_pk_bf16_f32 v81, v78, v79
	s_nop 0
	v_cvt_pk_bf16_f32 v82, v72, v73
	v_cvt_pk_bf16_f32 v83, v74, v75
	global_store_dwordx4 v[84:85], v[80:83], off
	s_nop 0
	s_nop 0
	s_nop 0
	s_waitcnt vmcnt(6)
	v_mov_b64_e32 v[80:81], v[216:217]
	v_mov_b64_e32 v[82:83], v[218:219]
	s_mov_b32 s98, 0x58000
	v_lshl_add_u64 v[200:201], v[198:199], 0, s[98:99]
	global_load_dwordx4 v[216:219], v[200:201], off
	v_lshlrev_b32_e32 v86, 16, v80
	v_mov_b32_e32 v89, v205
	v_fmamk_f32 v89, v89, 0x3a800000, v182
	v_sqrt_f32_e32 v90, v89
	v_and_b32_e32 v87, 0xffff0000, v80
	v_lshlrev_b32_e32 v80, 16, v81
	v_and_b32_e32 v81, 0xffff0000, v81
	v_lshlrev_b32_e32 v88, 16, v82
	v_and_b32_e32 v89, 0xffff0000, v82
	v_lshlrev_b32_e32 v82, 16, v83
	v_and_b32_e32 v83, 0xffff0000, v83
	v_pk_mul_f32 v[86:87], v[90:91], v[86:87] op_sel_hi:[0,1]
	v_pk_mul_f32 v[80:81], v[90:91], v[80:81] op_sel_hi:[0,1]
	v_pk_mul_f32 v[88:89], v[90:91], v[88:89] op_sel_hi:[0,1]
	v_pk_mul_f32 v[82:83], v[90:91], v[82:83] op_sel_hi:[0,1]
	v_pk_fma_f32 v[70:71], v[126:127], v[80:81], v[70:71]
	v_pk_fma_f32 v[68:69], v[122:123], v[86:87], v[68:69]
	v_pk_fma_f32 v[66:67], v[124:125], v[82:83], v[66:67]
	v_pk_fma_f32 v[64:65], v[120:121], v[88:89], v[64:65]
	v_cvt_pk_bf16_f32 v80, v68, v69
	v_cvt_pk_bf16_f32 v81, v70, v71
	s_nop 0
	v_cvt_pk_bf16_f32 v82, v64, v65
	v_cvt_pk_bf16_f32 v83, v66, v67
	global_store_dwordx4 v[84:85], v[80:83], off offset:256
	s_cbranch_vccnz .LBB0_610
	v_mul_f32_e32 v72, v72, v72
	v_fmac_f32_e32 v72, v73, v73
	v_mul_f32_e32 v73, v76, v76
	v_mul_f32_e32 v68, v68, v68
	v_mul_f32_e32 v64, v64, v64
	v_fmac_f32_e32 v73, v77, v77
	v_fmac_f32_e32 v68, v69, v69
	v_fmac_f32_e32 v64, v65, v65
	v_fmac_f32_e32 v72, v74, v74
	v_fmac_f32_e32 v73, v78, v78
	v_fmac_f32_e32 v68, v70, v70
	v_fmac_f32_e32 v64, v66, v66
	v_fmac_f32_e32 v72, v75, v75
	v_fmac_f32_e32 v73, v79, v79
	v_fmac_f32_e32 v68, v71, v71
	v_fmac_f32_e32 v64, v67, v67
	v_add_f32_e32 v72, v72, v73
	v_add_f32_e32 v64, v64, v68
	v_add_f32_e32 v64, v72, v64
	v_mov_b32_e32 v65, v64
	s_nop 1
	v_permlane16_swap_b32_e32 v64, v65
	v_add_f32_e32 v64, v64, v65
	v_mov_b32_e32 v65, v64
	s_nop 1
	v_permlane32_swap_b32_e32 v64, v65
	s_and_saveexec_b64 s[48:49], s[4:5]
	s_cbranch_execz .LBB0_609
	v_lshl_add_u64 v[66:67], v[152:153], 2, s[12:13]
	v_add_f32_e32 v64, v64, v65
	v_mov_b32_e32 v249, v64

.LBB0_610:
	s_nop 0
	v_lshl_add_u64 v[68:69], v[164:165], 1, v[144:145]
	v_lshl_add_u64 v[70:71], s[18:19], 0, v[68:69]
	s_nop 0
	v_lshl_add_u64 v[68:69], s[20:21], 0, v[68:69]
	s_and_b64 vcc, exec, s[8:9]
	v_mov_b32_e32 v72, v206
	v_fmamk_f32 v72, v72, 0x3a800000, v182
	v_sqrt_f32_e32 v72, v72
	s_waitcnt vmcnt(6)
	v_mov_b64_e32 v[64:65], v[220:221]
	v_mov_b64_e32 v[66:67], v[222:223]
	s_mov_b32 s98, 0x58000
	v_lshl_add_u64 v[200:201], v[198:199], 0, s[98:99]
	global_load_dwordx4 v[220:223], v[200:201], off offset:256
	v_lshlrev_b32_e32 v74, 16, v64
	v_and_b32_e32 v75, 0xffff0000, v64
	v_lshlrev_b32_e32 v64, 16, v65
	v_and_b32_e32 v65, 0xffff0000, v65
	v_lshlrev_b32_e32 v76, 16, v66
	v_and_b32_e32 v77, 0xffff0000, v66
	v_lshlrev_b32_e32 v66, 16, v67
	v_and_b32_e32 v67, 0xffff0000, v67
	v_pk_mul_f32 v[74:75], v[72:73], v[74:75] op_sel_hi:[0,1]
	v_pk_mul_f32 v[64:65], v[72:73], v[64:65] op_sel_hi:[0,1]
	v_pk_mul_f32 v[76:77], v[72:73], v[76:77] op_sel_hi:[0,1]
	v_pk_mul_f32 v[66:67], v[72:73], v[66:67] op_sel_hi:[0,1]
	v_pk_fma_f32 v[62:63], v[160:161], v[64:65], v[62:63]
	v_pk_fma_f32 v[60:61], v[156:157], v[74:75], v[60:61]
	v_pk_fma_f32 v[58:59], v[162:163], v[66:67], v[58:59]
	v_pk_fma_f32 v[56:57], v[158:159], v[76:77], v[56:57]
	v_cvt_pk_bf16_f32 v64, v60, v61
	v_cvt_pk_bf16_f32 v65, v62, v63
	s_nop 0
	v_cvt_pk_bf16_f32 v66, v56, v57
	v_cvt_pk_bf16_f32 v67, v58, v59
	global_store_dwordx4 v[68:69], v[64:67], off
	s_nop 0
	s_nop 0
	s_nop 0
	s_waitcnt vmcnt(6)
	v_mov_b64_e32 v[64:65], v[224:225]
	v_mov_b64_e32 v[66:67], v[226:227]
	v_lshlrev_b32_e32 v70, 16, v64
	v_mov_b32_e32 v73, v206
	v_fmamk_f32 v73, v73, 0x3a800000, v182
	v_sqrt_f32_e32 v74, v73
	v_and_b32_e32 v71, 0xffff0000, v64
	v_lshlrev_b32_e32 v64, 16, v65
	v_and_b32_e32 v65, 0xffff0000, v65
	v_lshlrev_b32_e32 v72, 16, v66
	v_and_b32_e32 v73, 0xffff0000, v66
	v_lshlrev_b32_e32 v66, 16, v67
	v_and_b32_e32 v67, 0xffff0000, v67
	v_pk_mul_f32 v[70:71], v[74:75], v[70:71] op_sel_hi:[0,1]
	v_pk_mul_f32 v[64:65], v[74:75], v[64:65] op_sel_hi:[0,1]
	v_pk_mul_f32 v[72:73], v[74:75], v[72:73] op_sel_hi:[0,1]
	v_pk_mul_f32 v[66:67], v[74:75], v[66:67] op_sel_hi:[0,1]
	v_pk_fma_f32 v[54:55], v[126:127], v[64:65], v[54:55]
	v_pk_fma_f32 v[52:53], v[122:123], v[70:71], v[52:53]
	v_pk_fma_f32 v[50:51], v[124:125], v[66:67], v[50:51]
	v_pk_fma_f32 v[48:49], v[120:121], v[72:73], v[48:49]
	v_cvt_pk_bf16_f32 v64, v52, v53
	v_cvt_pk_bf16_f32 v65, v54, v55
	s_nop 0
	v_cvt_pk_bf16_f32 v66, v48, v49
	v_cvt_pk_bf16_f32 v67, v50, v51
	global_store_dwordx4 v[68:69], v[64:67], off offset:256
	s_cbranch_vccnz .LBB0_614
	v_mul_f32_e32 v56, v56, v56
	v_fmac_f32_e32 v56, v57, v57
	v_mul_f32_e32 v57, v60, v60
	v_mul_f32_e32 v52, v52, v52
	v_mul_f32_e32 v48, v48, v48
	v_fmac_f32_e32 v57, v61, v61
	v_fmac_f32_e32 v52, v53, v53
	v_fmac_f32_e32 v48, v49, v49
	v_fmac_f32_e32 v56, v58, v58
	v_fmac_f32_e32 v57, v62, v62
	v_fmac_f32_e32 v52, v54, v54
	v_fmac_f32_e32 v48, v50, v50
	v_fmac_f32_e32 v56, v59, v59
	v_fmac_f32_e32 v57, v63, v63
	v_fmac_f32_e32 v52, v55, v55
	v_fmac_f32_e32 v48, v51, v51
	v_add_f32_e32 v56, v56, v57
	v_add_f32_e32 v48, v48, v52
	v_add_f32_e32 v48, v56, v48
	v_mov_b32_e32 v49, v48
	s_nop 1
	v_permlane16_swap_b32_e32 v48, v49
	v_add_f32_e32 v48, v48, v49
	v_mov_b32_e32 v49, v48
	s_nop 1
	v_permlane32_swap_b32_e32 v48, v49
	s_and_saveexec_b64 s[48:49], s[4:5]
	s_cbranch_execz .LBB0_613
	v_lshl_add_u64 v[50:51], v[152:153], 2, s[12:13]
	v_add_f32_e32 v48, v48, v49
	v_mov_b32_e32 v250, v48

.LBB0_614:
	s_nop 0
	v_lshl_add_u64 v[52:53], v[164:165], 1, v[146:147]
	v_lshl_add_u64 v[54:55], s[18:19], 0, v[52:53]
	s_nop 0
	v_lshl_add_u64 v[52:53], s[20:21], 0, v[52:53]
	s_and_b64 vcc, exec, s[8:9]
	v_mov_b32_e32 v56, v207
	v_fmamk_f32 v56, v56, 0x3a800000, v182
	v_sqrt_f32_e32 v56, v56
	s_waitcnt vmcnt(5)
	v_mov_b64_e32 v[48:49], v[228:229]
	v_mov_b64_e32 v[50:51], v[230:231]
	v_lshlrev_b32_e32 v58, 16, v48
	v_and_b32_e32 v59, 0xffff0000, v48
	v_lshlrev_b32_e32 v48, 16, v49
	v_and_b32_e32 v49, 0xffff0000, v49
	v_lshlrev_b32_e32 v60, 16, v50
	v_and_b32_e32 v61, 0xffff0000, v50
	v_lshlrev_b32_e32 v50, 16, v51
	v_and_b32_e32 v51, 0xffff0000, v51
	v_pk_mul_f32 v[58:59], v[56:57], v[58:59] op_sel_hi:[0,1]
	v_pk_mul_f32 v[48:49], v[56:57], v[48:49] op_sel_hi:[0,1]
	v_pk_mul_f32 v[60:61], v[56:57], v[60:61] op_sel_hi:[0,1]
	v_pk_mul_f32 v[50:51], v[56:57], v[50:51] op_sel_hi:[0,1]
	v_pk_fma_f32 v[46:47], v[160:161], v[48:49], v[46:47]
	v_pk_fma_f32 v[44:45], v[156:157], v[58:59], v[44:45]
	v_pk_fma_f32 v[42:43], v[162:163], v[50:51], v[42:43]
	v_pk_fma_f32 v[40:41], v[158:159], v[60:61], v[40:41]
	v_cvt_pk_bf16_f32 v48, v44, v45
	v_cvt_pk_bf16_f32 v49, v46, v47
	s_nop 0
	v_cvt_pk_bf16_f32 v50, v40, v41
	v_cvt_pk_bf16_f32 v51, v42, v43
	global_store_dwordx4 v[52:53], v[48:51], off
	s_nop 0
	s_nop 0
	s_nop 0
	s_waitcnt vmcnt(4)
	v_mov_b64_e32 v[48:49], v[232:233]
	v_mov_b64_e32 v[50:51], v[234:235]
	v_lshlrev_b32_e32 v54, 16, v48
	v_mov_b32_e32 v57, v207
	v_fmamk_f32 v57, v57, 0x3a800000, v182
	v_sqrt_f32_e32 v58, v57
	v_and_b32_e32 v55, 0xffff0000, v48
	v_lshlrev_b32_e32 v48, 16, v49
	v_and_b32_e32 v49, 0xffff0000, v49
	v_lshlrev_b32_e32 v56, 16, v50
	v_and_b32_e32 v57, 0xffff0000, v50
	v_lshlrev_b32_e32 v50, 16, v51
	v_and_b32_e32 v51, 0xffff0000, v51
	v_pk_mul_f32 v[54:55], v[58:59], v[54:55] op_sel_hi:[0,1]
	v_pk_mul_f32 v[48:49], v[58:59], v[48:49] op_sel_hi:[0,1]
	v_pk_mul_f32 v[56:57], v[58:59], v[56:57] op_sel_hi:[0,1]
	v_pk_mul_f32 v[50:51], v[58:59], v[50:51] op_sel_hi:[0,1]
	v_pk_fma_f32 v[38:39], v[126:127], v[48:49], v[38:39]
	v_pk_fma_f32 v[36:37], v[122:123], v[54:55], v[36:37]
	v_pk_fma_f32 v[34:35], v[124:125], v[50:51], v[34:35]
	v_pk_fma_f32 v[32:33], v[120:121], v[56:57], v[32:33]
	v_cvt_pk_bf16_f32 v48, v36, v37
	v_cvt_pk_bf16_f32 v49, v38, v39
	s_nop 0
	v_cvt_pk_bf16_f32 v50, v32, v33
	v_cvt_pk_bf16_f32 v51, v34, v35
	global_store_dwordx4 v[52:53], v[48:51], off offset:256
	s_cbranch_vccnz .LBB0_618
	v_mul_f32_e32 v40, v40, v40
	v_fmac_f32_e32 v40, v41, v41
	v_mul_f32_e32 v41, v44, v44
	v_mul_f32_e32 v36, v36, v36
	v_mul_f32_e32 v32, v32, v32
	v_fmac_f32_e32 v41, v45, v45
	v_fmac_f32_e32 v36, v37, v37
	v_fmac_f32_e32 v32, v33, v33
	v_fmac_f32_e32 v40, v42, v42
	v_fmac_f32_e32 v41, v46, v46
	v_fmac_f32_e32 v36, v38, v38
	v_fmac_f32_e32 v32, v34, v34
	v_fmac_f32_e32 v40, v43, v43
	v_fmac_f32_e32 v41, v47, v47
	v_fmac_f32_e32 v36, v39, v39
	v_fmac_f32_e32 v32, v35, v35
	v_add_f32_e32 v40, v40, v41
	v_add_f32_e32 v32, v32, v36
	v_add_f32_e32 v32, v40, v32
	v_mov_b32_e32 v33, v32
	s_nop 1
	v_permlane16_swap_b32_e32 v32, v33
	v_add_f32_e32 v32, v32, v33
	v_mov_b32_e32 v33, v32
	s_nop 1
	v_permlane32_swap_b32_e32 v32, v33
	s_and_saveexec_b64 s[48:49], s[4:5]
	s_cbranch_execz .LBB0_617
	v_lshl_add_u64 v[34:35], v[152:153], 2, s[12:13]
	v_add_f32_e32 v32, v32, v33
	v_mov_b32_e32 v251, v32

.LBB0_618:
	s_nop 0
	v_lshl_add_u64 v[36:37], v[164:165], 1, v[148:149]
	v_lshl_add_u64 v[38:39], s[18:19], 0, v[36:37]
	s_nop 0
	v_lshl_add_u64 v[36:37], s[20:21], 0, v[36:37]
	s_and_b64 vcc, exec, s[8:9]
	v_mov_b32_e32 v40, v212
	v_fmamk_f32 v40, v40, 0x3a800000, v182
	v_sqrt_f32_e32 v40, v40
	s_waitcnt vmcnt(3)
	v_mov_b64_e32 v[32:33], v[236:237]
	v_mov_b64_e32 v[34:35], v[238:239]
	v_lshlrev_b32_e32 v42, 16, v32
	v_and_b32_e32 v43, 0xffff0000, v32
	v_lshlrev_b32_e32 v32, 16, v33
	v_and_b32_e32 v33, 0xffff0000, v33
	v_lshlrev_b32_e32 v44, 16, v34
	v_and_b32_e32 v45, 0xffff0000, v34
	v_lshlrev_b32_e32 v34, 16, v35
	v_and_b32_e32 v35, 0xffff0000, v35
	v_pk_mul_f32 v[42:43], v[40:41], v[42:43] op_sel_hi:[0,1]
	v_pk_mul_f32 v[32:33], v[40:41], v[32:33] op_sel_hi:[0,1]
	v_pk_mul_f32 v[44:45], v[40:41], v[44:45] op_sel_hi:[0,1]
	v_pk_mul_f32 v[34:35], v[40:41], v[34:35] op_sel_hi:[0,1]
	v_pk_fma_f32 v[30:31], v[160:161], v[32:33], v[30:31]
	v_pk_fma_f32 v[28:29], v[156:157], v[42:43], v[28:29]
	v_pk_fma_f32 v[26:27], v[162:163], v[34:35], v[26:27]
	v_pk_fma_f32 v[24:25], v[158:159], v[44:45], v[24:25]
	v_cvt_pk_bf16_f32 v32, v28, v29
	v_cvt_pk_bf16_f32 v33, v30, v31
	s_nop 0
	v_cvt_pk_bf16_f32 v34, v24, v25
	v_cvt_pk_bf16_f32 v35, v26, v27
	global_store_dwordx4 v[36:37], v[32:35], off
	s_nop 0
	s_nop 0
	s_nop 0
	s_waitcnt vmcnt(2)
	v_mov_b64_e32 v[32:33], v[240:241]
	v_mov_b64_e32 v[34:35], v[242:243]
	v_lshlrev_b32_e32 v38, 16, v32
	v_mov_b32_e32 v41, v212
	v_fmamk_f32 v41, v41, 0x3a800000, v182
	v_sqrt_f32_e32 v42, v41
	v_and_b32_e32 v39, 0xffff0000, v32
	v_lshlrev_b32_e32 v32, 16, v33
	v_and_b32_e32 v33, 0xffff0000, v33
	v_lshlrev_b32_e32 v40, 16, v34
	v_and_b32_e32 v41, 0xffff0000, v34
	v_lshlrev_b32_e32 v34, 16, v35
	v_and_b32_e32 v35, 0xffff0000, v35
	v_pk_mul_f32 v[38:39], v[42:43], v[38:39] op_sel_hi:[0,1]
	v_pk_mul_f32 v[32:33], v[42:43], v[32:33] op_sel_hi:[0,1]
	v_pk_mul_f32 v[40:41], v[42:43], v[40:41] op_sel_hi:[0,1]
	v_pk_mul_f32 v[34:35], v[42:43], v[34:35] op_sel_hi:[0,1]
	v_pk_fma_f32 v[22:23], v[126:127], v[32:33], v[22:23]
	v_pk_fma_f32 v[20:21], v[122:123], v[38:39], v[20:21]
	v_pk_fma_f32 v[18:19], v[124:125], v[34:35], v[18:19]
	v_pk_fma_f32 v[16:17], v[120:121], v[40:41], v[16:17]
	v_cvt_pk_bf16_f32 v32, v20, v21
	v_cvt_pk_bf16_f32 v33, v22, v23
	s_nop 0
	v_cvt_pk_bf16_f32 v34, v16, v17
	v_cvt_pk_bf16_f32 v35, v18, v19
	global_store_dwordx4 v[36:37], v[32:35], off offset:256
	s_cbranch_vccnz .LBB0_622
	v_mul_f32_e32 v24, v24, v24
	v_fmac_f32_e32 v24, v25, v25
	v_mul_f32_e32 v25, v28, v28
	v_mul_f32_e32 v20, v20, v20
	v_mul_f32_e32 v16, v16, v16
	v_fmac_f32_e32 v25, v29, v29
	v_fmac_f32_e32 v20, v21, v21
	v_fmac_f32_e32 v16, v17, v17
	v_fmac_f32_e32 v24, v26, v26
	v_fmac_f32_e32 v25, v30, v30
	v_fmac_f32_e32 v20, v22, v22
	v_fmac_f32_e32 v16, v18, v18
	v_fmac_f32_e32 v24, v27, v27
	v_fmac_f32_e32 v25, v31, v31
	v_fmac_f32_e32 v20, v23, v23
	v_fmac_f32_e32 v16, v19, v19
	v_add_f32_e32 v24, v24, v25
	v_add_f32_e32 v16, v16, v20
	v_add_f32_e32 v16, v24, v16
	v_mov_b32_e32 v17, v16
	s_nop 1
	v_permlane16_swap_b32_e32 v16, v17
	v_add_f32_e32 v16, v16, v17
	v_mov_b32_e32 v17, v16
	s_nop 1
	v_permlane32_swap_b32_e32 v16, v17
	s_and_saveexec_b64 s[48:49], s[4:5]
	s_cbranch_execz .LBB0_621
	v_lshl_add_u64 v[18:19], v[152:153], 2, s[12:13]
	v_add_f32_e32 v16, v16, v17
	v_mov_b32_e32 v252, v16

.LBB0_622:
	s_nop 0
	v_lshl_add_u64 v[20:21], v[164:165], 1, v[150:151]
	v_lshl_add_u64 v[22:23], s[18:19], 0, v[20:21]
	s_nop 0
	v_lshl_add_u64 v[20:21], s[20:21], 0, v[20:21]
	s_and_b64 vcc, exec, s[8:9]
	v_mov_b32_e32 v24, v213
	v_fmamk_f32 v24, v24, 0x3a800000, v182
	v_sqrt_f32_e32 v24, v24
	s_waitcnt vmcnt(1)
	v_mov_b64_e32 v[16:17], v[216:217]
	v_mov_b64_e32 v[18:19], v[218:219]
	v_lshlrev_b32_e32 v26, 16, v16
	v_and_b32_e32 v27, 0xffff0000, v16
	v_lshlrev_b32_e32 v16, 16, v17
	v_and_b32_e32 v17, 0xffff0000, v17
	v_lshlrev_b32_e32 v28, 16, v18
	v_and_b32_e32 v29, 0xffff0000, v18
	v_lshlrev_b32_e32 v18, 16, v19
	v_and_b32_e32 v19, 0xffff0000, v19
	v_pk_mul_f32 v[26:27], v[24:25], v[26:27] op_sel_hi:[0,1]
	v_pk_mul_f32 v[16:17], v[24:25], v[16:17] op_sel_hi:[0,1]
	v_pk_mul_f32 v[28:29], v[24:25], v[28:29] op_sel_hi:[0,1]
	v_pk_mul_f32 v[18:19], v[24:25], v[18:19] op_sel_hi:[0,1]
	v_pk_fma_f32 v[14:15], v[160:161], v[16:17], v[14:15]
	v_pk_fma_f32 v[12:13], v[156:157], v[26:27], v[12:13]
	v_pk_fma_f32 v[10:11], v[162:163], v[18:19], v[10:11]
	v_pk_fma_f32 v[8:9], v[158:159], v[28:29], v[8:9]
	v_cvt_pk_bf16_f32 v16, v12, v13
	v_cvt_pk_bf16_f32 v17, v14, v15
	s_nop 0
	v_cvt_pk_bf16_f32 v18, v8, v9
	v_cvt_pk_bf16_f32 v19, v10, v11
	global_store_dwordx4 v[20:21], v[16:19], off
	s_nop 0
	s_nop 0
	s_nop 0
	s_waitcnt vmcnt(0)
	v_mov_b64_e32 v[16:17], v[220:221]
	v_mov_b64_e32 v[18:19], v[222:223]
	v_lshlrev_b32_e32 v22, 16, v16
	v_mov_b32_e32 v25, v213
	v_fmamk_f32 v25, v25, 0x3a800000, v182
	v_sqrt_f32_e32 v26, v25
	v_and_b32_e32 v23, 0xffff0000, v16
	v_lshlrev_b32_e32 v16, 16, v17
	v_and_b32_e32 v17, 0xffff0000, v17
	v_lshlrev_b32_e32 v24, 16, v18
	v_and_b32_e32 v25, 0xffff0000, v18
	v_lshlrev_b32_e32 v18, 16, v19
	v_and_b32_e32 v19, 0xffff0000, v19
	v_pk_mul_f32 v[22:23], v[26:27], v[22:23] op_sel_hi:[0,1]
	v_pk_mul_f32 v[16:17], v[26:27], v[16:17] op_sel_hi:[0,1]
	v_pk_mul_f32 v[24:25], v[26:27], v[24:25] op_sel_hi:[0,1]
	v_pk_mul_f32 v[18:19], v[26:27], v[18:19] op_sel_hi:[0,1]
	v_pk_fma_f32 v[6:7], v[126:127], v[16:17], v[6:7]
	v_pk_fma_f32 v[4:5], v[122:123], v[22:23], v[4:5]
	v_pk_fma_f32 v[2:3], v[124:125], v[18:19], v[2:3]
	v_pk_fma_f32 v[0:1], v[120:121], v[24:25], v[0:1]
	v_cvt_pk_bf16_f32 v16, v4, v5
	v_cvt_pk_bf16_f32 v17, v6, v7
	s_nop 0
	v_cvt_pk_bf16_f32 v18, v0, v1
	v_cvt_pk_bf16_f32 v19, v2, v3
	global_store_dwordx4 v[20:21], v[16:19], off offset:256
	s_cbranch_vccnz .LBB0_626
	v_mul_f32_e32 v8, v8, v8
	v_fmac_f32_e32 v8, v9, v9
	v_mul_f32_e32 v9, v12, v12
	v_mul_f32_e32 v4, v4, v4
	v_mul_f32_e32 v0, v0, v0
	v_fmac_f32_e32 v9, v13, v13
	v_fmac_f32_e32 v4, v5, v5
	v_fmac_f32_e32 v0, v1, v1
	v_fmac_f32_e32 v8, v10, v10
	v_fmac_f32_e32 v9, v14, v14
	v_fmac_f32_e32 v4, v6, v6
	v_fmac_f32_e32 v0, v2, v2
	v_fmac_f32_e32 v8, v11, v11
	v_fmac_f32_e32 v9, v15, v15
	v_fmac_f32_e32 v4, v7, v7
	v_fmac_f32_e32 v0, v3, v3
	v_add_f32_e32 v8, v8, v9
	v_add_f32_e32 v0, v0, v4
	v_add_f32_e32 v0, v8, v0
	v_mov_b32_e32 v1, v0
	s_nop 1
	v_permlane16_swap_b32_e32 v0, v1
	v_add_f32_e32 v0, v0, v1
	v_mov_b32_e32 v1, v0
	s_nop 1
	v_permlane32_swap_b32_e32 v0, v1
	s_and_saveexec_b64 s[8:9], s[4:5]
	s_cbranch_execz .LBB0_625
	v_lshl_add_u64 v[2:3], v[152:153], 2, s[12:13]
	v_add_f32_e32 v0, v0, v1
	global_atomic_add_f32 v[244:245], v214, off
	global_atomic_add_f32 v[244:245], v215, off offset:64
	global_atomic_add_f32 v[244:245], v248, off offset:128
	global_atomic_add_f32 v[244:245], v249, off offset:192
	global_atomic_add_f32 v[244:245], v250, off offset:512
	global_atomic_add_f32 v[244:245], v251, off offset:576
	global_atomic_add_f32 v[244:245], v252, off offset:640
	global_atomic_add_f32 v[2:3], v0, off offset:704

.LBB0_786:
	v_lshl_add_u32 v144, s8, 8, v151
	v_ashrrev_i32_e32 v145, 31, v144
	v_cndmask_b32_e64 v146, 0, 1, s[36:37]
	v_cmp_ne_u32_e64 s[8:9], 1, v146
	s_andn2_b64 vcc, exec, s[36:37]
	v_lshl_add_u64 v[148:149], v[144:145], 2, s[12:13]
	v_lshl_or_b32 v234, s46, 8, v153
	v_ashrrev_i32_e32 v235, 31, v234
	v_lshlrev_b64 v[170:171], 10, v[144:145]
	v_lshl_add_u64 v[170:171], v[170:171], 0, v[234:235]
	v_lshlrev_b64 v[170:171], 1, v[170:171]
	v_lshl_add_u64 v[170:171], s[16:17], 0, v[170:171]
	s_mov_b32 s99, 0
	s_and_b64 vcc, exec, s[36:37]
	s_cbranch_vccz .Lp5_nostat
	global_load_dword v238, v[148:149], off
	global_load_dword v239, v[148:149], off offset:64
	global_load_dword v240, v[148:149], off offset:128
	global_load_dword v241, v[148:149], off offset:192
	global_load_dword v242, v[148:149], off offset:512
	global_load_dword v243, v[148:149], off offset:576
	global_load_dword v244, v[148:149], off offset:640
	global_load_dword v245, v[148:149], off offset:704
.Lp5_nostat:
	global_load_dwordx4 v[172:175], v[170:171], off
	global_load_dwordx4 v[176:179], v[170:171], off offset:256
	s_mov_b32 s98, 0x8000
	v_lshl_add_u64 v[232:233], v[170:171], 0, s[98:99]
	global_load_dwordx4 v[180:183], v[232:233], off
	s_mov_b32 s98, 0x8000
	v_lshl_add_u64 v[232:233], v[170:171], 0, s[98:99]
	global_load_dwordx4 v[184:187], v[232:233], off offset:256
	s_mov_b32 s98, 0x10000
	v_lshl_add_u64 v[232:233], v[170:171], 0, s[98:99]
	global_load_dwordx4 v[188:191], v[232:233], off
	s_mov_b32 s98, 0x10000
	v_lshl_add_u64 v[232:233], v[170:171], 0, s[98:99]
	global_load_dwordx4 v[192:195], v[232:233], off offset:256
	s_mov_b32 s98, 0x18000
	v_lshl_add_u64 v[232:233], v[170:171], 0, s[98:99]
	global_load_dwordx4 v[196:199], v[232:233], off
	s_mov_b32 s98, 0x18000
	v_lshl_add_u64 v[232:233], v[170:171], 0, s[98:99]
	global_load_dwordx4 v[200:203], v[232:233], off offset:256
	s_mov_b32 s98, 0x40000
	v_lshl_add_u64 v[232:233], v[170:171], 0, s[98:99]
	global_load_dwordx4 v[204:207], v[232:233], off
	s_mov_b32 s98, 0x40000
	v_lshl_add_u64 v[232:233], v[170:171], 0, s[98:99]
	global_load_dwordx4 v[212:215], v[232:233], off offset:256
	s_mov_b32 s98, 0x48000
	v_lshl_add_u64 v[232:233], v[170:171], 0, s[98:99]
	global_load_dwordx4 v[216:219], v[232:233], off
	s_mov_b32 s98, 0x48000
	v_lshl_add_u64 v[232:233], v[170:171], 0, s[98:99]
	global_load_dwordx4 v[220:223], v[232:233], off offset:256
	s_mov_b32 s98, 0x50000
	v_lshl_add_u64 v[232:233], v[170:171], 0, s[98:99]
	global_load_dwordx4 v[224:227], v[232:233], off
	s_mov_b32 s98, 0x50000
	v_lshl_add_u64 v[232:233], v[170:171], 0, s[98:99]
	global_load_dwordx4 v[228:231], v[232:233], off offset:256
	s_andn2_b64 vcc, exec, s[36:37]
	s_cbranch_vccnz .LBB0_788
	s_nop 0
	s_waitcnt vmcnt(14)
	v_mov_b32_e32 v146, v238
	v_fmamk_f32 v146, v146, 0x3a800000, v157
	v_rcp_f32_e32 v150, v146
	s_branch .LBB0_789

.LBB0_789:
	v_lshl_or_b32 v146, s46, 8, v153
	v_ashrrev_i32_e32 v147, 31, v146
	v_lshlrev_b64 v[158:159], 10, v[144:145]
	v_lshl_add_u64 v[158:159], v[158:159], 0, v[146:147]
	v_lshlrev_b64 v[162:163], 1, v[158:159]
	v_lshl_add_u64 v[164:165], s[16:17], 0, v[162:163]
	s_nop 0
	v_lshl_add_u64 v[162:163], s[18:19], 0, v[162:163]
	s_waitcnt vmcnt(13)
	v_mov_b64_e32 v[158:159], v[172:173]
	v_mov_b64_e32 v[160:161], v[174:175]
	s_mov_b32 s98, 0x58000
	v_lshl_add_u64 v[232:233], v[170:171], 0, s[98:99]
	global_load_dwordx4 v[172:175], v[232:233], off
	v_lshlrev_b32_e32 v166, 16, v158
	v_and_b32_e32 v167, 0xffff0000, v158
	v_lshlrev_b32_e32 v158, 16, v159
	v_and_b32_e32 v159, 0xffff0000, v159
	v_lshlrev_b32_e32 v168, 16, v160
	v_and_b32_e32 v169, 0xffff0000, v160
	v_lshlrev_b32_e32 v160, 16, v161
	v_and_b32_e32 v161, 0xffff0000, v161
	v_pk_fma_f32 v[126:127], v[126:127], v[150:151], v[158:159] op_sel_hi:[1,0,1]
	v_pk_fma_f32 v[124:125], v[124:125], v[150:151], v[166:167] op_sel_hi:[1,0,1]
	v_pk_fma_f32 v[158:159], v[122:123], v[150:151], v[160:161] op_sel_hi:[1,0,1]
	v_pk_fma_f32 v[160:161], v[120:121], v[150:151], v[168:169] op_sel_hi:[1,0,1]
	v_cvt_pk_bf16_f32 v120, v124, v125
	v_cvt_pk_bf16_f32 v121, v126, v127
	v_mul_f32_e32 v124, v124, v124
	v_cvt_pk_bf16_f32 v122, v160, v161
	v_cvt_pk_bf16_f32 v123, v158, v159
	global_store_dwordx4 v[162:163], v[120:123], off
	s_nop 0
	v_mul_f32_e32 v160, v160, v160
	v_fmac_f32_e32 v124, v125, v125
	v_fmac_f32_e32 v160, v161, v161
	v_fmac_f32_e32 v124, v126, v126
	v_fmac_f32_e32 v160, v158, v158
	v_fmac_f32_e32 v124, v127, v127
	v_fmac_f32_e32 v160, v159, v159
	v_add_f32_e32 v158, v160, v124
	s_waitcnt vmcnt(13)
	v_mov_b64_e32 v[120:121], v[176:177]
	v_mov_b64_e32 v[122:123], v[178:179]
	s_mov_b32 s98, 0x58000
	v_lshl_add_u64 v[232:233], v[170:171], 0, s[98:99]
	global_load_dwordx4 v[176:179], v[232:233], off offset:256
	v_lshlrev_b32_e32 v124, 16, v120
	v_and_b32_e32 v125, 0xffff0000, v120
	v_lshlrev_b32_e32 v120, 16, v121
	v_and_b32_e32 v121, 0xffff0000, v121
	v_lshlrev_b32_e32 v126, 16, v122
	v_and_b32_e32 v127, 0xffff0000, v122
	v_lshlrev_b32_e32 v122, 16, v123
	v_and_b32_e32 v123, 0xffff0000, v123
	v_pk_fma_f32 v[118:119], v[118:119], v[150:151], v[120:121] op_sel_hi:[1,0,1]
	v_pk_fma_f32 v[116:117], v[116:117], v[150:151], v[124:125] op_sel_hi:[1,0,1]
	v_pk_fma_f32 v[120:121], v[114:115], v[150:151], v[122:123] op_sel_hi:[1,0,1]
	v_pk_fma_f32 v[122:123], v[112:113], v[150:151], v[126:127] op_sel_hi:[1,0,1]
	v_cvt_pk_bf16_f32 v112, v116, v117
	v_cvt_pk_bf16_f32 v113, v118, v119
	v_mul_f32_e32 v116, v116, v116
	v_cvt_pk_bf16_f32 v114, v122, v123
	v_mul_f32_e32 v122, v122, v122
	v_fmac_f32_e32 v116, v117, v117
	v_fmac_f32_e32 v122, v123, v123
	v_fmac_f32_e32 v116, v118, v118
	v_fmac_f32_e32 v122, v120, v120
	v_fmac_f32_e32 v116, v119, v119
	v_fmac_f32_e32 v122, v121, v121
	v_cvt_pk_bf16_f32 v115, v120, v121
	global_store_dwordx4 v[162:163], v[112:115], off offset:256
	s_nop 1
	v_add_f32_e32 v112, v122, v116
	v_add_f32_e32 v112, v158, v112
	v_mov_b32_e32 v113, v112
	s_nop 1
	v_permlane16_swap_b32_e32 v112, v113
	v_add_f32_e32 v112, v112, v113
	v_mov_b32_e32 v113, v112
	s_nop 1
	v_permlane32_swap_b32_e32 v112, v113
	s_and_saveexec_b64 s[46:47], s[4:5]
	s_cbranch_execz .LBB0_791
	v_lshl_add_u64 v[114:115], v[144:145], 2, s[20:21]
	v_mov_b64_e32 v[236:237], v[114:115]
	v_add_f32_e32 v112, v112, v113
	v_mov_b32_e32 v246, v112
.LBB0_791:
	s_or_b64 exec, exec, s[46:47]
	s_and_b64 vcc, exec, s[8:9]
	s_cbranch_vccnz .LBB0_793
	s_nop 0
	v_mov_b32_e32 v112, v239
	v_fmamk_f32 v112, v112, 0x3a800000, v157
	v_rcp_f32_e32 v114, v112
	s_branch .LBB0_794

.LBB0_794:
	v_or_b32_e32 v112, 16, v144
	v_ashrrev_i32_e32 v113, 31, v112
	v_lshlrev_b64 v[116:117], 10, v[112:113]
	v_lshl_add_u64 v[116:117], v[116:117], 0, v[146:147]
	v_lshlrev_b64 v[120:121], 1, v[116:117]
	v_lshl_add_u64 v[122:123], s[16:17], 0, v[120:121]
	s_nop 0
	v_lshl_add_u64 v[120:121], s[18:19], 0, v[120:121]
	s_waitcnt vmcnt(13)
	v_mov_b64_e32 v[116:117], v[180:181]
	v_mov_b64_e32 v[118:119], v[182:183]
	v_lshlrev_b32_e32 v124, 16, v116
	v_and_b32_e32 v125, 0xffff0000, v116
	v_lshlrev_b32_e32 v116, 16, v117
	v_and_b32_e32 v117, 0xffff0000, v117
	v_lshlrev_b32_e32 v126, 16, v118
	v_and_b32_e32 v127, 0xffff0000, v118
	v_lshlrev_b32_e32 v118, 16, v119
	v_and_b32_e32 v119, 0xffff0000, v119
	v_pk_fma_f32 v[110:111], v[110:111], v[114:115], v[116:117] op_sel_hi:[1,0,1]
	v_pk_fma_f32 v[108:109], v[108:109], v[114:115], v[124:125] op_sel_hi:[1,0,1]
	v_pk_fma_f32 v[116:117], v[106:107], v[114:115], v[118:119] op_sel_hi:[1,0,1]
	v_pk_fma_f32 v[118:119], v[104:105], v[114:115], v[126:127] op_sel_hi:[1,0,1]
	v_cvt_pk_bf16_f32 v104, v108, v109
	v_cvt_pk_bf16_f32 v105, v110, v111
	v_mul_f32_e32 v108, v108, v108
	v_cvt_pk_bf16_f32 v106, v118, v119
	v_cvt_pk_bf16_f32 v107, v116, v117
	global_store_dwordx4 v[120:121], v[104:107], off
	s_nop 0
	v_mul_f32_e32 v115, v118, v118
	v_fmac_f32_e32 v108, v109, v109
	v_fmac_f32_e32 v115, v119, v119
	v_fmac_f32_e32 v108, v110, v110
	v_fmac_f32_e32 v115, v116, v116
	v_fmac_f32_e32 v108, v111, v111
	v_fmac_f32_e32 v115, v117, v117
	v_add_f32_e32 v115, v115, v108
	s_waitcnt vmcnt(12)
	v_mov_b64_e32 v[104:105], v[184:185]
	v_mov_b64_e32 v[106:107], v[186:187]
	v_lshlrev_b32_e32 v108, 16, v104
	v_and_b32_e32 v109, 0xffff0000, v104
	v_lshlrev_b32_e32 v104, 16, v105
	v_and_b32_e32 v105, 0xffff0000, v105
	v_lshlrev_b32_e32 v110, 16, v106
	v_and_b32_e32 v111, 0xffff0000, v106
	v_lshlrev_b32_e32 v106, 16, v107
	v_and_b32_e32 v107, 0xffff0000, v107
	v_pk_fma_f32 v[102:103], v[102:103], v[114:115], v[104:105] op_sel_hi:[1,0,1]
	v_pk_fma_f32 v[100:101], v[100:101], v[114:115], v[108:109] op_sel_hi:[1,0,1]
	v_pk_fma_f32 v[104:105], v[98:99], v[114:115], v[106:107] op_sel_hi:[1,0,1]
	v_pk_fma_f32 v[106:107], v[96:97], v[114:115], v[110:111] op_sel_hi:[1,0,1]
	v_cvt_pk_bf16_f32 v96, v100, v101
	v_cvt_pk_bf16_f32 v97, v102, v103
	v_mul_f32_e32 v100, v100, v100
	v_cvt_pk_bf16_f32 v98, v106, v107
	v_mul_f32_e32 v106, v106, v106
	v_fmac_f32_e32 v100, v101, v101
	v_fmac_f32_e32 v106, v107, v107
	v_fmac_f32_e32 v100, v102, v102
	v_fmac_f32_e32 v106, v104, v104
	v_fmac_f32_e32 v100, v103, v103
	v_fmac_f32_e32 v106, v105, v105
	v_cvt_pk_bf16_f32 v99, v104, v105
	global_store_dwordx4 v[120:121], v[96:99], off offset:256
	s_nop 1
	v_add_f32_e32 v96, v106, v100
	v_add_f32_e32 v96, v115, v96
	v_mov_b32_e32 v97, v96
	s_nop 1
	v_permlane16_swap_b32_e32 v96, v97
	v_add_f32_e32 v96, v96, v97
	v_mov_b32_e32 v97, v96
	s_nop 1
	v_permlane32_swap_b32_e32 v96, v97
	s_and_saveexec_b64 s[46:47], s[4:5]
	s_cbranch_execz .LBB0_796
	v_lshl_add_u64 v[98:99], v[112:113], 2, s[20:21]
	v_add_f32_e32 v96, v96, v97
	v_mov_b32_e32 v247, v96
.LBB0_796:
	s_or_b64 exec, exec, s[46:47]
	s_and_b64 vcc, exec, s[8:9]
	s_cbranch_vccnz .LBB0_798
	s_nop 0
	v_mov_b32_e32 v96, v240
	v_fmamk_f32 v96, v96, 0x3a800000, v157
	v_rcp_f32_e32 v98, v96
	s_branch .LBB0_799

.LBB0_799:
	v_or_b32_e32 v96, 32, v144
	v_ashrrev_i32_e32 v97, 31, v96
	v_lshlrev_b64 v[100:101], 10, v[96:97]
	v_lshl_add_u64 v[100:101], v[100:101], 0, v[146:147]
	v_lshlrev_b64 v[104:105], 1, v[100:101]
	v_lshl_add_u64 v[106:107], s[16:17], 0, v[104:105]
	s_nop 0
	v_lshl_add_u64 v[104:105], s[18:19], 0, v[104:105]
	s_waitcnt vmcnt(11)
	v_mov_b64_e32 v[100:101], v[188:189]
	v_mov_b64_e32 v[102:103], v[190:191]
	v_lshlrev_b32_e32 v108, 16, v100
	v_and_b32_e32 v109, 0xffff0000, v100
	v_lshlrev_b32_e32 v100, 16, v101
	v_and_b32_e32 v101, 0xffff0000, v101
	v_lshlrev_b32_e32 v110, 16, v102
	v_and_b32_e32 v111, 0xffff0000, v102
	v_lshlrev_b32_e32 v102, 16, v103
	v_and_b32_e32 v103, 0xffff0000, v103
	v_pk_fma_f32 v[94:95], v[94:95], v[98:99], v[100:101] op_sel_hi:[1,0,1]
	v_pk_fma_f32 v[92:93], v[92:93], v[98:99], v[108:109] op_sel_hi:[1,0,1]
	v_pk_fma_f32 v[100:101], v[90:91], v[98:99], v[102:103] op_sel_hi:[1,0,1]
	v_pk_fma_f32 v[102:103], v[88:89], v[98:99], v[110:111] op_sel_hi:[1,0,1]
	v_cvt_pk_bf16_f32 v88, v92, v93
	v_cvt_pk_bf16_f32 v89, v94, v95
	v_mul_f32_e32 v92, v92, v92
	v_cvt_pk_bf16_f32 v90, v102, v103
	v_cvt_pk_bf16_f32 v91, v100, v101
	global_store_dwordx4 v[104:105], v[88:91], off
	s_nop 0
	v_mul_f32_e32 v99, v102, v102
	v_fmac_f32_e32 v92, v93, v93
	v_fmac_f32_e32 v99, v103, v103
	v_fmac_f32_e32 v92, v94, v94
	v_fmac_f32_e32 v99, v100, v100
	v_fmac_f32_e32 v92, v95, v95
	v_fmac_f32_e32 v99, v101, v101
	v_add_f32_e32 v99, v99, v92
	s_waitcnt vmcnt(10)
	v_mov_b64_e32 v[88:89], v[192:193]
	v_mov_b64_e32 v[90:91], v[194:195]
	v_lshlrev_b32_e32 v92, 16, v88
	v_and_b32_e32 v93, 0xffff0000, v88
	v_lshlrev_b32_e32 v88, 16, v89
	v_and_b32_e32 v89, 0xffff0000, v89
	v_lshlrev_b32_e32 v94, 16, v90
	v_and_b32_e32 v95, 0xffff0000, v90
	v_lshlrev_b32_e32 v90, 16, v91
	v_and_b32_e32 v91, 0xffff0000, v91
	v_pk_fma_f32 v[86:87], v[86:87], v[98:99], v[88:89] op_sel_hi:[1,0,1]
	v_pk_fma_f32 v[84:85], v[84:85], v[98:99], v[92:93] op_sel_hi:[1,0,1]
	v_pk_fma_f32 v[88:89], v[82:83], v[98:99], v[90:91] op_sel_hi:[1,0,1]
	v_pk_fma_f32 v[90:91], v[80:81], v[98:99], v[94:95] op_sel_hi:[1,0,1]
	v_cvt_pk_bf16_f32 v80, v84, v85
	v_cvt_pk_bf16_f32 v81, v86, v87
	v_mul_f32_e32 v84, v84, v84
	v_cvt_pk_bf16_f32 v82, v90, v91
	v_mul_f32_e32 v90, v90, v90
	v_fmac_f32_e32 v84, v85, v85
	v_fmac_f32_e32 v90, v91, v91
	v_fmac_f32_e32 v84, v86, v86
	v_fmac_f32_e32 v90, v88, v88
	v_fmac_f32_e32 v84, v87, v87
	v_fmac_f32_e32 v90, v89, v89
	v_cvt_pk_bf16_f32 v83, v88, v89
	global_store_dwordx4 v[104:105], v[80:83], off offset:256
	s_nop 1
	v_add_f32_e32 v80, v90, v84
	v_add_f32_e32 v80, v99, v80
	v_mov_b32_e32 v81, v80
	s_nop 1
	v_permlane16_swap_b32_e32 v80, v81
	v_add_f32_e32 v80, v80, v81
	v_mov_b32_e32 v81, v80
	s_nop 1
	v_permlane32_swap_b32_e32 v80, v81
	s_and_saveexec_b64 s[46:47], s[4:5]
	s_cbranch_execz .LBB0_801
	v_lshl_add_u64 v[82:83], v[96:97], 2, s[20:21]
	v_add_f32_e32 v80, v80, v81
	v_mov_b32_e32 v248, v80
.LBB0_801:
	s_or_b64 exec, exec, s[46:47]
	s_and_b64 vcc, exec, s[8:9]
	s_cbranch_vccnz .LBB0_803
	s_nop 0
	v_mov_b32_e32 v80, v241
	v_fmamk_f32 v80, v80, 0x3a800000, v157
	v_rcp_f32_e32 v82, v80
	s_branch .LBB0_804

.LBB0_804:
	v_or_b32_e32 v80, 48, v144
	v_ashrrev_i32_e32 v81, 31, v80
	v_lshlrev_b64 v[84:85], 10, v[80:81]
	v_lshl_add_u64 v[84:85], v[84:85], 0, v[146:147]
	v_lshlrev_b64 v[88:89], 1, v[84:85]
	v_lshl_add_u64 v[90:91], s[16:17], 0, v[88:89]
	s_nop 0
	v_lshl_add_u64 v[88:89], s[18:19], 0, v[88:89]
	s_waitcnt vmcnt(9)
	v_mov_b64_e32 v[84:85], v[196:197]
	v_mov_b64_e32 v[86:87], v[198:199]
	v_lshlrev_b32_e32 v92, 16, v84
	v_and_b32_e32 v93, 0xffff0000, v84
	v_lshlrev_b32_e32 v84, 16, v85
	v_and_b32_e32 v85, 0xffff0000, v85
	v_lshlrev_b32_e32 v94, 16, v86
	v_and_b32_e32 v95, 0xffff0000, v86
	v_lshlrev_b32_e32 v86, 16, v87
	v_and_b32_e32 v87, 0xffff0000, v87
	v_pk_fma_f32 v[78:79], v[78:79], v[82:83], v[84:85] op_sel_hi:[1,0,1]
	v_pk_fma_f32 v[76:77], v[76:77], v[82:83], v[92:93] op_sel_hi:[1,0,1]
	v_pk_fma_f32 v[84:85], v[74:75], v[82:83], v[86:87] op_sel_hi:[1,0,1]
	v_pk_fma_f32 v[86:87], v[72:73], v[82:83], v[94:95] op_sel_hi:[1,0,1]
	v_cvt_pk_bf16_f32 v72, v76, v77
	v_cvt_pk_bf16_f32 v73, v78, v79
	v_mul_f32_e32 v76, v76, v76
	v_cvt_pk_bf16_f32 v74, v86, v87
	v_cvt_pk_bf16_f32 v75, v84, v85
	global_store_dwordx4 v[88:89], v[72:75], off
	s_nop 0
	v_mul_f32_e32 v83, v86, v86
	v_fmac_f32_e32 v76, v77, v77
	v_fmac_f32_e32 v83, v87, v87
	v_fmac_f32_e32 v76, v78, v78
	v_fmac_f32_e32 v83, v84, v84
	v_fmac_f32_e32 v76, v79, v79
	v_fmac_f32_e32 v83, v85, v85
	v_add_f32_e32 v83, v83, v76
	s_waitcnt vmcnt(8)
	v_mov_b64_e32 v[72:73], v[200:201]
	v_mov_b64_e32 v[74:75], v[202:203]
	v_lshlrev_b32_e32 v76, 16, v72
	v_and_b32_e32 v77, 0xffff0000, v72
	v_lshlrev_b32_e32 v72, 16, v73
	v_and_b32_e32 v73, 0xffff0000, v73
	v_lshlrev_b32_e32 v78, 16, v74
	v_and_b32_e32 v79, 0xffff0000, v74
	v_lshlrev_b32_e32 v74, 16, v75
	v_and_b32_e32 v75, 0xffff0000, v75
	v_pk_fma_f32 v[70:71], v[70:71], v[82:83], v[72:73] op_sel_hi:[1,0,1]
	v_pk_fma_f32 v[68:69], v[68:69], v[82:83], v[76:77] op_sel_hi:[1,0,1]
	v_pk_fma_f32 v[72:73], v[66:67], v[82:83], v[74:75] op_sel_hi:[1,0,1]
	v_pk_fma_f32 v[74:75], v[64:65], v[82:83], v[78:79] op_sel_hi:[1,0,1]
	v_cvt_pk_bf16_f32 v64, v68, v69
	v_cvt_pk_bf16_f32 v65, v70, v71
	v_mul_f32_e32 v68, v68, v68
	v_cvt_pk_bf16_f32 v66, v74, v75
	v_mul_f32_e32 v74, v74, v74
	v_fmac_f32_e32 v68, v69, v69
	v_fmac_f32_e32 v74, v75, v75
	v_fmac_f32_e32 v68, v70, v70
	v_fmac_f32_e32 v74, v72, v72
	v_fmac_f32_e32 v68, v71, v71
	v_fmac_f32_e32 v74, v73, v73
	v_cvt_pk_bf16_f32 v67, v72, v73
	global_store_dwordx4 v[88:89], v[64:67], off offset:256
	s_nop 1
	v_add_f32_e32 v64, v74, v68
	v_add_f32_e32 v64, v83, v64
	v_mov_b32_e32 v65, v64
	s_nop 1
	v_permlane16_swap_b32_e32 v64, v65
	v_add_f32_e32 v64, v64, v65
	v_mov_b32_e32 v65, v64
	s_nop 1
	v_permlane32_swap_b32_e32 v64, v65
	s_and_saveexec_b64 s[46:47], s[4:5]
	s_cbranch_execz .LBB0_806
	v_lshl_add_u64 v[66:67], v[80:81], 2, s[20:21]
	v_add_f32_e32 v64, v64, v65
	v_mov_b32_e32 v249, v64
.LBB0_806:
	s_or_b64 exec, exec, s[46:47]
	s_and_b64 vcc, exec, s[8:9]
	s_cbranch_vccnz .LBB0_808
	s_nop 0
	v_mov_b32_e32 v64, v242
	v_fmamk_f32 v64, v64, 0x3a800000, v157
	v_rcp_f32_e32 v66, v64
	s_branch .LBB0_809

.LBB0_809:
	v_add_u32_e32 v64, 0x80, v144
	v_ashrrev_i32_e32 v65, 31, v64
	v_lshlrev_b64 v[68:69], 10, v[64:65]
	v_lshl_add_u64 v[68:69], v[68:69], 0, v[146:147]
	v_lshlrev_b64 v[72:73], 1, v[68:69]
	v_lshl_add_u64 v[74:75], s[16:17], 0, v[72:73]
	s_nop 0
	v_lshl_add_u64 v[72:73], s[18:19], 0, v[72:73]
	s_waitcnt vmcnt(7)
	v_mov_b64_e32 v[68:69], v[204:205]
	v_mov_b64_e32 v[70:71], v[206:207]
	v_lshlrev_b32_e32 v76, 16, v68
	v_and_b32_e32 v77, 0xffff0000, v68
	v_lshlrev_b32_e32 v68, 16, v69
	v_and_b32_e32 v69, 0xffff0000, v69
	v_lshlrev_b32_e32 v78, 16, v70
	v_and_b32_e32 v79, 0xffff0000, v70
	v_lshlrev_b32_e32 v70, 16, v71
	v_and_b32_e32 v71, 0xffff0000, v71
	v_pk_fma_f32 v[62:63], v[62:63], v[66:67], v[68:69] op_sel_hi:[1,0,1]
	v_pk_fma_f32 v[60:61], v[60:61], v[66:67], v[76:77] op_sel_hi:[1,0,1]
	v_pk_fma_f32 v[68:69], v[58:59], v[66:67], v[70:71] op_sel_hi:[1,0,1]
	v_pk_fma_f32 v[70:71], v[56:57], v[66:67], v[78:79] op_sel_hi:[1,0,1]
	v_cvt_pk_bf16_f32 v56, v60, v61
	v_cvt_pk_bf16_f32 v57, v62, v63
	v_mul_f32_e32 v60, v60, v60
	v_cvt_pk_bf16_f32 v58, v70, v71
	v_cvt_pk_bf16_f32 v59, v68, v69
	global_store_dwordx4 v[72:73], v[56:59], off
	s_nop 0
	v_mul_f32_e32 v67, v70, v70
	v_fmac_f32_e32 v60, v61, v61
	v_fmac_f32_e32 v67, v71, v71
	v_fmac_f32_e32 v60, v62, v62
	v_fmac_f32_e32 v67, v68, v68
	v_fmac_f32_e32 v60, v63, v63
	v_fmac_f32_e32 v67, v69, v69
	v_add_f32_e32 v67, v67, v60
	s_waitcnt vmcnt(6)
	v_mov_b64_e32 v[56:57], v[212:213]
	v_mov_b64_e32 v[58:59], v[214:215]
	v_lshlrev_b32_e32 v60, 16, v56
	v_and_b32_e32 v61, 0xffff0000, v56
	v_lshlrev_b32_e32 v56, 16, v57
	v_and_b32_e32 v57, 0xffff0000, v57
	v_lshlrev_b32_e32 v62, 16, v58
	v_and_b32_e32 v63, 0xffff0000, v58
	v_lshlrev_b32_e32 v58, 16, v59
	v_and_b32_e32 v59, 0xffff0000, v59
	v_pk_fma_f32 v[54:55], v[54:55], v[66:67], v[56:57] op_sel_hi:[1,0,1]
	v_pk_fma_f32 v[52:53], v[52:53], v[66:67], v[60:61] op_sel_hi:[1,0,1]
	v_pk_fma_f32 v[56:57], v[50:51], v[66:67], v[58:59] op_sel_hi:[1,0,1]
	v_pk_fma_f32 v[58:59], v[48:49], v[66:67], v[62:63] op_sel_hi:[1,0,1]
	v_cvt_pk_bf16_f32 v48, v52, v53
	v_cvt_pk_bf16_f32 v49, v54, v55
	v_mul_f32_e32 v52, v52, v52
	v_cvt_pk_bf16_f32 v50, v58, v59
	v_mul_f32_e32 v58, v58, v58
	v_fmac_f32_e32 v52, v53, v53
	v_fmac_f32_e32 v58, v59, v59
	v_fmac_f32_e32 v52, v54, v54
	v_fmac_f32_e32 v58, v56, v56
	v_fmac_f32_e32 v52, v55, v55
	v_fmac_f32_e32 v58, v57, v57
	v_cvt_pk_bf16_f32 v51, v56, v57
	global_store_dwordx4 v[72:73], v[48:51], off offset:256
	s_nop 1
	v_add_f32_e32 v48, v58, v52
	v_add_f32_e32 v48, v67, v48
	v_mov_b32_e32 v49, v48
	s_nop 1
	v_permlane16_swap_b32_e32 v48, v49
	v_add_f32_e32 v48, v48, v49
	v_mov_b32_e32 v49, v48
	s_nop 1
	v_permlane32_swap_b32_e32 v48, v49
	s_and_saveexec_b64 s[46:47], s[4:5]
	s_cbranch_execz .LBB0_811
	v_lshl_add_u64 v[50:51], v[64:65], 2, s[20:21]
	v_add_f32_e32 v48, v48, v49
	v_mov_b32_e32 v250, v48
.LBB0_811:
	s_or_b64 exec, exec, s[46:47]
	s_and_b64 vcc, exec, s[8:9]
	s_cbranch_vccnz .LBB0_813
	s_nop 0
	v_mov_b32_e32 v48, v243
	v_fmamk_f32 v48, v48, 0x3a800000, v157
	v_rcp_f32_e32 v50, v48
	s_branch .LBB0_814

.LBB0_814:
	v_add_u32_e32 v48, 0x90, v144
	v_ashrrev_i32_e32 v49, 31, v48
	v_lshlrev_b64 v[52:53], 10, v[48:49]
	v_lshl_add_u64 v[52:53], v[52:53], 0, v[146:147]
	v_lshlrev_b64 v[56:57], 1, v[52:53]
	v_lshl_add_u64 v[58:59], s[16:17], 0, v[56:57]
	s_nop 0
	v_lshl_add_u64 v[56:57], s[18:19], 0, v[56:57]
	s_waitcnt vmcnt(5)
	v_mov_b64_e32 v[52:53], v[216:217]
	v_mov_b64_e32 v[54:55], v[218:219]
	v_lshlrev_b32_e32 v60, 16, v52
	v_and_b32_e32 v61, 0xffff0000, v52
	v_lshlrev_b32_e32 v52, 16, v53
	v_and_b32_e32 v53, 0xffff0000, v53
	v_lshlrev_b32_e32 v62, 16, v54
	v_and_b32_e32 v63, 0xffff0000, v54
	v_lshlrev_b32_e32 v54, 16, v55
	v_and_b32_e32 v55, 0xffff0000, v55
	v_pk_fma_f32 v[46:47], v[46:47], v[50:51], v[52:53] op_sel_hi:[1,0,1]
	v_pk_fma_f32 v[44:45], v[44:45], v[50:51], v[60:61] op_sel_hi:[1,0,1]
	v_pk_fma_f32 v[52:53], v[42:43], v[50:51], v[54:55] op_sel_hi:[1,0,1]
	v_pk_fma_f32 v[54:55], v[40:41], v[50:51], v[62:63] op_sel_hi:[1,0,1]
	v_cvt_pk_bf16_f32 v40, v44, v45
	v_cvt_pk_bf16_f32 v41, v46, v47
	v_mul_f32_e32 v44, v44, v44
	v_cvt_pk_bf16_f32 v42, v54, v55
	v_cvt_pk_bf16_f32 v43, v52, v53
	global_store_dwordx4 v[56:57], v[40:43], off
	s_nop 0
	v_mul_f32_e32 v51, v54, v54
	v_fmac_f32_e32 v44, v45, v45
	v_fmac_f32_e32 v51, v55, v55
	v_fmac_f32_e32 v44, v46, v46
	v_fmac_f32_e32 v51, v52, v52
	v_fmac_f32_e32 v44, v47, v47
	v_fmac_f32_e32 v51, v53, v53
	v_add_f32_e32 v51, v51, v44
	s_waitcnt vmcnt(4)
	v_mov_b64_e32 v[40:41], v[220:221]
	v_mov_b64_e32 v[42:43], v[222:223]
	v_lshlrev_b32_e32 v44, 16, v40
	v_and_b32_e32 v45, 0xffff0000, v40
	v_lshlrev_b32_e32 v40, 16, v41
	v_and_b32_e32 v41, 0xffff0000, v41
	v_lshlrev_b32_e32 v46, 16, v42
	v_and_b32_e32 v47, 0xffff0000, v42
	v_lshlrev_b32_e32 v42, 16, v43
	v_and_b32_e32 v43, 0xffff0000, v43
	v_pk_fma_f32 v[38:39], v[38:39], v[50:51], v[40:41] op_sel_hi:[1,0,1]
	v_pk_fma_f32 v[36:37], v[36:37], v[50:51], v[44:45] op_sel_hi:[1,0,1]
	v_pk_fma_f32 v[40:41], v[34:35], v[50:51], v[42:43] op_sel_hi:[1,0,1]
	v_pk_fma_f32 v[42:43], v[32:33], v[50:51], v[46:47] op_sel_hi:[1,0,1]
	v_cvt_pk_bf16_f32 v32, v36, v37
	v_cvt_pk_bf16_f32 v33, v38, v39
	v_mul_f32_e32 v36, v36, v36
	v_cvt_pk_bf16_f32 v34, v42, v43
	v_mul_f32_e32 v42, v42, v42
	v_fmac_f32_e32 v36, v37, v37
	v_fmac_f32_e32 v42, v43, v43
	v_fmac_f32_e32 v36, v38, v38
	v_fmac_f32_e32 v42, v40, v40
	v_fmac_f32_e32 v36, v39, v39
	v_fmac_f32_e32 v42, v41, v41
	v_cvt_pk_bf16_f32 v35, v40, v41
	global_store_dwordx4 v[56:57], v[32:35], off offset:256
	s_nop 1
	v_add_f32_e32 v32, v42, v36
	v_add_f32_e32 v32, v51, v32
	v_mov_b32_e32 v33, v32
	s_nop 1
	v_permlane16_swap_b32_e32 v32, v33
	v_add_f32_e32 v32, v32, v33
	v_mov_b32_e32 v33, v32
	s_nop 1
	v_permlane32_swap_b32_e32 v32, v33
	s_and_saveexec_b64 s[46:47], s[4:5]
	s_cbranch_execz .LBB0_816
	v_lshl_add_u64 v[34:35], v[48:49], 2, s[20:21]
	v_add_f32_e32 v32, v32, v33
	v_mov_b32_e32 v251, v32
.LBB0_816:
	s_or_b64 exec, exec, s[46:47]
	s_and_b64 vcc, exec, s[8:9]
	s_cbranch_vccnz .LBB0_818
	s_nop 0
	v_mov_b32_e32 v32, v244
	v_fmamk_f32 v32, v32, 0x3a800000, v157
	v_rcp_f32_e32 v34, v32
	s_branch .LBB0_819

.LBB0_819:
	v_add_u32_e32 v32, 0xa0, v144
	v_ashrrev_i32_e32 v33, 31, v32
	v_lshlrev_b64 v[36:37], 10, v[32:33]
	v_lshl_add_u64 v[36:37], v[36:37], 0, v[146:147]
	v_lshlrev_b64 v[40:41], 1, v[36:37]
	v_lshl_add_u64 v[42:43], s[16:17], 0, v[40:41]
	s_nop 0
	v_lshl_add_u64 v[40:41], s[18:19], 0, v[40:41]
	s_waitcnt vmcnt(3)
	v_mov_b64_e32 v[36:37], v[224:225]
	v_mov_b64_e32 v[38:39], v[226:227]
	v_lshlrev_b32_e32 v44, 16, v36
	v_and_b32_e32 v45, 0xffff0000, v36
	v_lshlrev_b32_e32 v36, 16, v37
	v_and_b32_e32 v37, 0xffff0000, v37
	v_lshlrev_b32_e32 v46, 16, v38
	v_and_b32_e32 v47, 0xffff0000, v38
	v_lshlrev_b32_e32 v38, 16, v39
	v_and_b32_e32 v39, 0xffff0000, v39
	v_pk_fma_f32 v[30:31], v[30:31], v[34:35], v[36:37] op_sel_hi:[1,0,1]
	v_pk_fma_f32 v[28:29], v[28:29], v[34:35], v[44:45] op_sel_hi:[1,0,1]
	v_pk_fma_f32 v[36:37], v[26:27], v[34:35], v[38:39] op_sel_hi:[1,0,1]
	v_pk_fma_f32 v[38:39], v[24:25], v[34:35], v[46:47] op_sel_hi:[1,0,1]
	v_cvt_pk_bf16_f32 v24, v28, v29
	v_cvt_pk_bf16_f32 v25, v30, v31
	v_mul_f32_e32 v28, v28, v28
	v_cvt_pk_bf16_f32 v26, v38, v39
	v_cvt_pk_bf16_f32 v27, v36, v37
	global_store_dwordx4 v[40:41], v[24:27], off
	s_nop 0
	v_mul_f32_e32 v35, v38, v38
	v_fmac_f32_e32 v28, v29, v29
	v_fmac_f32_e32 v35, v39, v39
	v_fmac_f32_e32 v28, v30, v30
	v_fmac_f32_e32 v35, v36, v36
	v_fmac_f32_e32 v28, v31, v31
	v_fmac_f32_e32 v35, v37, v37
	v_add_f32_e32 v35, v35, v28
	s_waitcnt vmcnt(2)
	v_mov_b64_e32 v[24:25], v[228:229]
	v_mov_b64_e32 v[26:27], v[230:231]
	v_lshlrev_b32_e32 v28, 16, v24
	v_and_b32_e32 v29, 0xffff0000, v24
	v_lshlrev_b32_e32 v24, 16, v25
	v_and_b32_e32 v25, 0xffff0000, v25
	v_lshlrev_b32_e32 v30, 16, v26
	v_and_b32_e32 v31, 0xffff0000, v26
	v_lshlrev_b32_e32 v26, 16, v27
	v_and_b32_e32 v27, 0xffff0000, v27
	v_pk_fma_f32 v[22:23], v[22:23], v[34:35], v[24:25] op_sel_hi:[1,0,1]
	v_pk_fma_f32 v[20:21], v[20:21], v[34:35], v[28:29] op_sel_hi:[1,0,1]
	v_pk_fma_f32 v[24:25], v[18:19], v[34:35], v[26:27] op_sel_hi:[1,0,1]
	v_pk_fma_f32 v[26:27], v[16:17], v[34:35], v[30:31] op_sel_hi:[1,0,1]
	v_cvt_pk_bf16_f32 v16, v20, v21
	v_cvt_pk_bf16_f32 v17, v22, v23
	v_mul_f32_e32 v20, v20, v20
	v_cvt_pk_bf16_f32 v18, v26, v27
	v_mul_f32_e32 v26, v26, v26
	v_fmac_f32_e32 v20, v21, v21
	v_fmac_f32_e32 v26, v27, v27
	v_fmac_f32_e32 v20, v22, v22
	v_fmac_f32_e32 v26, v24, v24
	v_fmac_f32_e32 v20, v23, v23
	v_fmac_f32_e32 v26, v25, v25
	v_cvt_pk_bf16_f32 v19, v24, v25
	global_store_dwordx4 v[40:41], v[16:19], off offset:256
	s_nop 1
	v_add_f32_e32 v16, v26, v20
	v_add_f32_e32 v16, v35, v16
	v_mov_b32_e32 v17, v16
	s_nop 1
	v_permlane16_swap_b32_e32 v16, v17
	v_add_f32_e32 v16, v16, v17
	v_mov_b32_e32 v17, v16
	s_nop 1
	v_permlane32_swap_b32_e32 v16, v17
	s_and_saveexec_b64 s[46:47], s[4:5]
	s_cbranch_execz .LBB0_821
	v_lshl_add_u64 v[18:19], v[32:33], 2, s[20:21]
	v_add_f32_e32 v16, v16, v17
	v_mov_b32_e32 v252, v16
.LBB0_821:
	s_or_b64 exec, exec, s[46:47]
	s_and_b64 vcc, exec, s[8:9]
	s_cbranch_vccnz .LBB0_823
	s_nop 0
	v_mov_b32_e32 v16, v245
	v_fmamk_f32 v16, v16, 0x3a800000, v157
	v_rcp_f32_e32 v18, v16
	s_branch .LBB0_824

.LBB0_824:
	v_add_u32_e32 v16, 0xb0, v144
	v_ashrrev_i32_e32 v17, 31, v16
	v_lshlrev_b64 v[20:21], 10, v[16:17]
	v_lshl_add_u64 v[20:21], v[20:21], 0, v[146:147]
	v_lshlrev_b64 v[24:25], 1, v[20:21]
	v_lshl_add_u64 v[26:27], s[16:17], 0, v[24:25]
	s_nop 0
	v_lshl_add_u64 v[24:25], s[18:19], 0, v[24:25]
	s_waitcnt vmcnt(1)
	v_mov_b64_e32 v[20:21], v[172:173]
	v_mov_b64_e32 v[22:23], v[174:175]
	v_lshlrev_b32_e32 v28, 16, v20
	v_and_b32_e32 v29, 0xffff0000, v20
	v_lshlrev_b32_e32 v20, 16, v21
	v_and_b32_e32 v21, 0xffff0000, v21
	v_lshlrev_b32_e32 v30, 16, v22
	v_and_b32_e32 v31, 0xffff0000, v22
	v_lshlrev_b32_e32 v22, 16, v23
	v_and_b32_e32 v23, 0xffff0000, v23
	v_pk_fma_f32 v[14:15], v[14:15], v[18:19], v[20:21] op_sel_hi:[1,0,1]
	v_pk_fma_f32 v[12:13], v[12:13], v[18:19], v[28:29] op_sel_hi:[1,0,1]
	v_pk_fma_f32 v[20:21], v[10:11], v[18:19], v[22:23] op_sel_hi:[1,0,1]
	v_pk_fma_f32 v[22:23], v[8:9], v[18:19], v[30:31] op_sel_hi:[1,0,1]
	v_cvt_pk_bf16_f32 v8, v12, v13
	v_cvt_pk_bf16_f32 v9, v14, v15
	v_mul_f32_e32 v12, v12, v12
	v_cvt_pk_bf16_f32 v10, v22, v23
	v_cvt_pk_bf16_f32 v11, v20, v21
	global_store_dwordx4 v[24:25], v[8:11], off
	s_nop 0
	v_mul_f32_e32 v19, v22, v22
	v_fmac_f32_e32 v12, v13, v13
	v_fmac_f32_e32 v19, v23, v23
	v_fmac_f32_e32 v12, v14, v14
	v_fmac_f32_e32 v19, v20, v20
	v_fmac_f32_e32 v12, v15, v15
	v_fmac_f32_e32 v19, v21, v21
	v_add_f32_e32 v19, v19, v12
	s_waitcnt vmcnt(0)
	v_mov_b64_e32 v[8:9], v[176:177]
	v_mov_b64_e32 v[10:11], v[178:179]
	v_lshlrev_b32_e32 v12, 16, v8
	v_and_b32_e32 v13, 0xffff0000, v8
	v_lshlrev_b32_e32 v8, 16, v9
	v_and_b32_e32 v9, 0xffff0000, v9
	v_lshlrev_b32_e32 v14, 16, v10
	v_and_b32_e32 v15, 0xffff0000, v10
	v_lshlrev_b32_e32 v10, 16, v11
	v_and_b32_e32 v11, 0xffff0000, v11
	v_pk_fma_f32 v[6:7], v[6:7], v[18:19], v[8:9] op_sel_hi:[1,0,1]
	v_pk_fma_f32 v[4:5], v[4:5], v[18:19], v[12:13] op_sel_hi:[1,0,1]
	v_pk_fma_f32 v[8:9], v[2:3], v[18:19], v[10:11] op_sel_hi:[1,0,1]
	v_pk_fma_f32 v[10:11], v[0:1], v[18:19], v[14:15] op_sel_hi:[1,0,1]
	v_cvt_pk_bf16_f32 v0, v4, v5
	v_cvt_pk_bf16_f32 v1, v6, v7
	v_mul_f32_e32 v4, v4, v4
	v_cvt_pk_bf16_f32 v2, v10, v11
	v_mul_f32_e32 v10, v10, v10
	v_fmac_f32_e32 v4, v5, v5
	v_fmac_f32_e32 v10, v11, v11
	v_fmac_f32_e32 v4, v6, v6
	v_fmac_f32_e32 v10, v8, v8
	v_fmac_f32_e32 v4, v7, v7
	v_fmac_f32_e32 v10, v9, v9
	v_cvt_pk_bf16_f32 v3, v8, v9
	global_store_dwordx4 v[24:25], v[0:3], off offset:256
	s_nop 1
	v_add_f32_e32 v0, v10, v4
	v_add_f32_e32 v0, v19, v0
	v_mov_b32_e32 v1, v0
	s_nop 1
	v_permlane16_swap_b32_e32 v0, v1
	v_add_f32_e32 v0, v0, v1
	v_mov_b32_e32 v1, v0
	s_nop 1
	v_permlane32_swap_b32_e32 v0, v1
	s_and_saveexec_b64 s[8:9], s[4:5]
	s_cbranch_execz .LBB0_826
	v_lshl_add_u64 v[2:3], v[16:17], 2, s[20:21]
	v_add_f32_e32 v0, v0, v1
	global_atomic_add_f32 v[236:237], v246, off
	global_atomic_add_f32 v[236:237], v247, off offset:64
	global_atomic_add_f32 v[236:237], v248, off offset:128
	global_atomic_add_f32 v[236:237], v249, off offset:192
	global_atomic_add_f32 v[236:237], v250, off offset:512
	global_atomic_add_f32 v[236:237], v251, off offset:576
	global_atomic_add_f32 v[236:237], v252, off offset:640
	global_atomic_add_f32 v[2:3], v0, off

.LBB0_1230:
	v_lshl_add_u32 v146, s38, 8, v148
	v_ashrrev_i32_e32 v147, 31, v146
	v_lshl_or_b32 v144, s40, 7, v150
	v_lshlrev_b64 v[154:155], 11, v[146:147]
	v_ashrrev_i32_e32 v145, 31, v144
	v_lshl_add_u64 v[154:155], s[12:13], 0, v[154:155]
	v_lshl_add_u64 v[158:159], v[144:145], 1, v[154:155]
	v_mov_b64_e32 v[164:165], v[158:159]
	s_mov_b32 s99, 0
	global_load_dwordx4 v[180:183], v[164:165], off
	s_mov_b32 s98, 0x8000
	v_lshl_add_u64 v[166:167], v[164:165], 0, s[98:99]
	global_load_dwordx4 v[184:187], v[166:167], off
	s_mov_b32 s98, 0x10000
	v_lshl_add_u64 v[166:167], v[164:165], 0, s[98:99]
	global_load_dwordx4 v[188:191], v[166:167], off
	s_mov_b32 s98, 0x18000
	v_lshl_add_u64 v[166:167], v[164:165], 0, s[98:99]
	global_load_dwordx4 v[192:195], v[166:167], off
	s_mov_b32 s98, 0x40000
	v_lshl_add_u64 v[166:167], v[164:165], 0, s[98:99]
	global_load_dwordx4 v[196:199], v[166:167], off
	s_mov_b32 s98, 0x48000
	v_lshl_add_u64 v[166:167], v[164:165], 0, s[98:99]
	global_load_dwordx4 v[200:203], v[166:167], off
	s_mov_b32 s98, 0x50000
	v_lshl_add_u64 v[166:167], v[164:165], 0, s[98:99]
	global_load_dwordx4 v[204:207], v[166:167], off
	s_mov_b32 s98, 0x58000
	v_lshl_add_u64 v[166:167], v[164:165], 0, s[98:99]
	global_load_dwordx4 v[212:215], v[166:167], off
	s_nop 0
	v_mul_f32_e32 v124, 0xbfb8aa3b, v124
	v_mul_f32_e32 v116, 0xbfb8aa3b, v116
	v_mul_f32_e32 v125, 0xbfb8aa3b, v125
	v_mul_f32_e32 v117, 0xbfb8aa3b, v117
	v_exp_f32_e32 v124, v124
	v_exp_f32_e32 v116, v116
	v_mul_f32_e32 v126, 0xbfb8aa3b, v126
	v_mul_f32_e32 v118, 0xbfb8aa3b, v118
	v_exp_f32_e32 v125, v125
	v_exp_f32_e32 v117, v117
	v_mul_f32_e32 v127, 0xbfb8aa3b, v127
	v_mul_f32_e32 v119, 0xbfb8aa3b, v119
	v_exp_f32_e32 v126, v126
	v_exp_f32_e32 v118, v118
	v_exp_f32_e32 v127, v127
	v_exp_f32_e32 v119, v119
	v_add_f32_e32 v124, 1.0, v124
	v_add_f32_e32 v116, 1.0, v116
	v_add_f32_e32 v125, 1.0, v125
	v_add_f32_e32 v117, 1.0, v117
	v_rcp_f32_e32 v124, v124
	v_rcp_f32_e32 v116, v116
	v_add_f32_e32 v126, 1.0, v126
	v_add_f32_e32 v118, 1.0, v118
	v_rcp_f32_e32 v125, v125
	v_rcp_f32_e32 v117, v117
	v_add_f32_e32 v127, 1.0, v127
	v_add_f32_e32 v119, 1.0, v119
	v_rcp_f32_e32 v126, v126
	v_rcp_f32_e32 v118, v118
	v_rcp_f32_e32 v127, v127
	v_rcp_f32_e32 v119, v119
	s_waitcnt vmcnt(7)
	v_mov_b64_e32 v[154:155], v[180:181]
	v_mov_b64_e32 v[156:157], v[182:183]
	v_lshlrev_b32_e32 v160, 16, v154
	v_lshlrev_b32_e32 v162, 16, v156
	v_and_b32_e32 v154, 0xffff0000, v154
	v_and_b32_e32 v156, 0xffff0000, v156
	v_fmac_f32_e32 v160, v120, v124
	v_fmac_f32_e32 v162, v112, v116
	v_lshlrev_b32_e32 v161, 16, v155
	v_lshlrev_b32_e32 v163, 16, v157
	v_fmac_f32_e32 v154, v121, v125
	v_fmac_f32_e32 v156, v113, v117
	v_mul_f32_e32 v116, v160, v160
	v_mul_f32_e32 v117, v162, v162
	v_and_b32_e32 v155, 0xffff0000, v155
	v_and_b32_e32 v157, 0xffff0000, v157
	v_fmac_f32_e32 v161, v122, v126
	v_fmac_f32_e32 v163, v114, v118
	v_fmac_f32_e32 v116, v154, v154
	v_fmac_f32_e32 v117, v156, v156
	v_fmac_f32_e32 v155, v123, v127
	v_fmac_f32_e32 v157, v115, v119
	v_fmac_f32_e32 v116, v161, v161
	v_fmac_f32_e32 v117, v163, v163
	v_cvt_pk_bf16_f32 v112, v160, v154
	v_fmac_f32_e32 v116, v155, v155
	v_fmac_f32_e32 v117, v157, v157
	v_cvt_pk_bf16_f32 v113, v161, v155
	v_cvt_pk_bf16_f32 v114, v162, v156
	v_cvt_pk_bf16_f32 v115, v163, v157
	global_store_dwordx4 v[158:159], v[112:115], off
	s_nop 1
	v_add_f32_e32 v112, v116, v117
	v_mov_b32_e32 v113, v112
	s_nop 1
	v_permlane16_swap_b32_e32 v112, v113
	v_add_f32_e32 v112, v112, v113
	v_mov_b32_e32 v113, v112
	s_nop 1
	v_permlane32_swap_b32_e32 v112, v113
	s_and_saveexec_b64 s[38:39], s[4:5]
	s_cbranch_execz .LBB0_1232
	v_add_f32_e32 v114, v112, v113
	v_lshl_add_u64 v[112:113], v[146:147], 2, s[14:15]
	v_mov_b64_e32 v[168:169], v[112:113]
	v_mov_b32_e32 v170, v114
.LBB0_1232:
	s_or_b64 exec, exec, s[38:39]
	v_or_b32_e32 v112, 16, v146
	v_ashrrev_i32_e32 v113, 31, v112
	v_lshlrev_b64 v[114:115], 11, v[112:113]
	v_lshl_add_u64 v[114:115], s[12:13], 0, v[114:115]
	v_lshl_add_u64 v[118:119], v[144:145], 1, v[114:115]
	s_nop 0
	v_mul_f32_e32 v108, 0xbfb8aa3b, v108
	v_mul_f32_e32 v100, 0xbfb8aa3b, v100
	v_mul_f32_e32 v109, 0xbfb8aa3b, v109
	v_mul_f32_e32 v101, 0xbfb8aa3b, v101
	v_exp_f32_e32 v108, v108
	v_exp_f32_e32 v100, v100
	v_mul_f32_e32 v110, 0xbfb8aa3b, v110
	v_mul_f32_e32 v102, 0xbfb8aa3b, v102
	v_exp_f32_e32 v109, v109
	v_exp_f32_e32 v101, v101
	v_mul_f32_e32 v111, 0xbfb8aa3b, v111
	v_mul_f32_e32 v103, 0xbfb8aa3b, v103
	v_exp_f32_e32 v110, v110
	v_exp_f32_e32 v102, v102
	v_exp_f32_e32 v111, v111
	v_exp_f32_e32 v103, v103
	v_add_f32_e32 v108, 1.0, v108
	v_add_f32_e32 v100, 1.0, v100
	v_add_f32_e32 v109, 1.0, v109
	v_add_f32_e32 v101, 1.0, v101
	v_rcp_f32_e32 v108, v108
	v_rcp_f32_e32 v100, v100
	v_add_f32_e32 v110, 1.0, v110
	v_add_f32_e32 v102, 1.0, v102
	v_rcp_f32_e32 v109, v109
	v_rcp_f32_e32 v101, v101
	v_add_f32_e32 v111, 1.0, v111
	v_add_f32_e32 v103, 1.0, v103
	v_rcp_f32_e32 v110, v110
	v_rcp_f32_e32 v102, v102
	v_rcp_f32_e32 v111, v111
	v_rcp_f32_e32 v103, v103
	s_waitcnt vmcnt(6)
	v_mov_b64_e32 v[114:115], v[184:185]
	v_mov_b64_e32 v[116:117], v[186:187]
	v_lshlrev_b32_e32 v120, 16, v114
	v_lshlrev_b32_e32 v122, 16, v116
	v_and_b32_e32 v114, 0xffff0000, v114
	v_and_b32_e32 v116, 0xffff0000, v116
	v_fmac_f32_e32 v120, v104, v108
	v_fmac_f32_e32 v122, v96, v100
	v_lshlrev_b32_e32 v121, 16, v115
	v_lshlrev_b32_e32 v123, 16, v117
	v_fmac_f32_e32 v114, v105, v109
	v_fmac_f32_e32 v116, v97, v101
	v_mul_f32_e32 v100, v120, v120
	v_mul_f32_e32 v101, v122, v122
	v_and_b32_e32 v115, 0xffff0000, v115
	v_and_b32_e32 v117, 0xffff0000, v117
	v_fmac_f32_e32 v121, v106, v110
	v_fmac_f32_e32 v123, v98, v102
	v_fmac_f32_e32 v100, v114, v114
	v_fmac_f32_e32 v101, v116, v116
	v_fmac_f32_e32 v115, v107, v111
	v_fmac_f32_e32 v117, v99, v103
	v_fmac_f32_e32 v100, v121, v121
	v_fmac_f32_e32 v101, v123, v123
	v_cvt_pk_bf16_f32 v96, v120, v114
	v_fmac_f32_e32 v100, v115, v115
	v_fmac_f32_e32 v101, v117, v117
	v_cvt_pk_bf16_f32 v97, v121, v115
	v_cvt_pk_bf16_f32 v98, v122, v116
	v_cvt_pk_bf16_f32 v99, v123, v117
	global_store_dwordx4 v[118:119], v[96:99], off
	s_nop 1
	v_add_f32_e32 v96, v100, v101
	v_mov_b32_e32 v97, v96
	s_nop 1
	v_permlane16_swap_b32_e32 v96, v97
	v_add_f32_e32 v96, v96, v97
	v_mov_b32_e32 v97, v96
	s_nop 1
	v_permlane32_swap_b32_e32 v96, v97
	s_and_saveexec_b64 s[38:39], s[4:5]
	s_cbranch_execz .LBB0_1234
	v_add_f32_e32 v98, v96, v97
	v_lshl_add_u64 v[96:97], v[112:113], 2, s[14:15]
	v_mov_b32_e32 v171, v98
.LBB0_1234:
	s_or_b64 exec, exec, s[38:39]
	v_or_b32_e32 v96, 32, v146
	v_ashrrev_i32_e32 v97, 31, v96
	v_lshlrev_b64 v[98:99], 11, v[96:97]
	v_lshl_add_u64 v[98:99], s[12:13], 0, v[98:99]
	v_lshl_add_u64 v[102:103], v[144:145], 1, v[98:99]
	s_nop 0
	v_mul_f32_e32 v92, 0xbfb8aa3b, v92
	v_mul_f32_e32 v84, 0xbfb8aa3b, v84
	v_mul_f32_e32 v93, 0xbfb8aa3b, v93
	v_mul_f32_e32 v85, 0xbfb8aa3b, v85
	v_exp_f32_e32 v92, v92
	v_exp_f32_e32 v84, v84
	v_mul_f32_e32 v94, 0xbfb8aa3b, v94
	v_mul_f32_e32 v86, 0xbfb8aa3b, v86
	v_exp_f32_e32 v93, v93
	v_exp_f32_e32 v85, v85
	v_mul_f32_e32 v95, 0xbfb8aa3b, v95
	v_mul_f32_e32 v87, 0xbfb8aa3b, v87
	v_exp_f32_e32 v94, v94
	v_exp_f32_e32 v86, v86
	v_exp_f32_e32 v95, v95
	v_exp_f32_e32 v87, v87
	v_add_f32_e32 v92, 1.0, v92
	v_add_f32_e32 v84, 1.0, v84
	v_add_f32_e32 v93, 1.0, v93
	v_add_f32_e32 v85, 1.0, v85
	v_rcp_f32_e32 v92, v92
	v_rcp_f32_e32 v84, v84
	v_add_f32_e32 v94, 1.0, v94
	v_add_f32_e32 v86, 1.0, v86
	v_rcp_f32_e32 v93, v93
	v_rcp_f32_e32 v85, v85
	v_add_f32_e32 v95, 1.0, v95
	v_add_f32_e32 v87, 1.0, v87
	v_rcp_f32_e32 v94, v94
	v_rcp_f32_e32 v86, v86
	v_rcp_f32_e32 v95, v95
	v_rcp_f32_e32 v87, v87
	s_waitcnt vmcnt(5)
	v_mov_b64_e32 v[98:99], v[188:189]
	v_mov_b64_e32 v[100:101], v[190:191]
	v_lshlrev_b32_e32 v104, 16, v98
	v_lshlrev_b32_e32 v106, 16, v100
	v_and_b32_e32 v98, 0xffff0000, v98
	v_and_b32_e32 v100, 0xffff0000, v100
	v_fmac_f32_e32 v104, v88, v92
	v_fmac_f32_e32 v106, v80, v84
	v_lshlrev_b32_e32 v105, 16, v99
	v_lshlrev_b32_e32 v107, 16, v101
	v_fmac_f32_e32 v98, v89, v93
	v_fmac_f32_e32 v100, v81, v85
	v_mul_f32_e32 v84, v104, v104
	v_mul_f32_e32 v85, v106, v106
	v_and_b32_e32 v99, 0xffff0000, v99
	v_and_b32_e32 v101, 0xffff0000, v101
	v_fmac_f32_e32 v105, v90, v94
	v_fmac_f32_e32 v107, v82, v86
	v_fmac_f32_e32 v84, v98, v98
	v_fmac_f32_e32 v85, v100, v100
	v_fmac_f32_e32 v99, v91, v95
	v_fmac_f32_e32 v101, v83, v87
	v_fmac_f32_e32 v84, v105, v105
	v_fmac_f32_e32 v85, v107, v107
	v_cvt_pk_bf16_f32 v80, v104, v98
	v_fmac_f32_e32 v84, v99, v99
	v_fmac_f32_e32 v85, v101, v101
	v_cvt_pk_bf16_f32 v81, v105, v99
	v_cvt_pk_bf16_f32 v82, v106, v100
	v_cvt_pk_bf16_f32 v83, v107, v101
	global_store_dwordx4 v[102:103], v[80:83], off
	s_nop 1
	v_add_f32_e32 v80, v84, v85
	v_mov_b32_e32 v81, v80
	s_nop 1
	v_permlane16_swap_b32_e32 v80, v81
	v_add_f32_e32 v80, v80, v81
	v_mov_b32_e32 v81, v80
	s_nop 1
	v_permlane32_swap_b32_e32 v80, v81
	s_and_saveexec_b64 s[38:39], s[4:5]
	s_cbranch_execz .LBB0_1236
	v_add_f32_e32 v82, v80, v81
	v_lshl_add_u64 v[80:81], v[96:97], 2, s[14:15]
	v_mov_b32_e32 v172, v82
.LBB0_1236:
	s_or_b64 exec, exec, s[38:39]
	v_or_b32_e32 v80, 48, v146
	v_ashrrev_i32_e32 v81, 31, v80
	v_lshlrev_b64 v[82:83], 11, v[80:81]
	v_lshl_add_u64 v[82:83], s[12:13], 0, v[82:83]
	v_lshl_add_u64 v[86:87], v[144:145], 1, v[82:83]
	s_nop 0
	v_mul_f32_e32 v76, 0xbfb8aa3b, v76
	v_mul_f32_e32 v68, 0xbfb8aa3b, v68
	v_mul_f32_e32 v77, 0xbfb8aa3b, v77
	v_mul_f32_e32 v69, 0xbfb8aa3b, v69
	v_exp_f32_e32 v76, v76
	v_exp_f32_e32 v68, v68
	v_mul_f32_e32 v78, 0xbfb8aa3b, v78
	v_mul_f32_e32 v70, 0xbfb8aa3b, v70
	v_exp_f32_e32 v77, v77
	v_exp_f32_e32 v69, v69
	v_mul_f32_e32 v79, 0xbfb8aa3b, v79
	v_mul_f32_e32 v71, 0xbfb8aa3b, v71
	v_exp_f32_e32 v78, v78
	v_exp_f32_e32 v70, v70
	v_exp_f32_e32 v79, v79
	v_exp_f32_e32 v71, v71
	v_add_f32_e32 v76, 1.0, v76
	v_add_f32_e32 v68, 1.0, v68
	v_add_f32_e32 v77, 1.0, v77
	v_add_f32_e32 v69, 1.0, v69
	v_rcp_f32_e32 v76, v76
	v_rcp_f32_e32 v68, v68
	v_add_f32_e32 v78, 1.0, v78
	v_add_f32_e32 v70, 1.0, v70
	v_rcp_f32_e32 v77, v77
	v_rcp_f32_e32 v69, v69
	v_add_f32_e32 v79, 1.0, v79
	v_add_f32_e32 v71, 1.0, v71
	v_rcp_f32_e32 v78, v78
	v_rcp_f32_e32 v70, v70
	v_rcp_f32_e32 v79, v79
	v_rcp_f32_e32 v71, v71
	s_waitcnt vmcnt(4)
	v_mov_b64_e32 v[82:83], v[192:193]
	v_mov_b64_e32 v[84:85], v[194:195]
	v_lshlrev_b32_e32 v88, 16, v82
	v_lshlrev_b32_e32 v90, 16, v84
	v_and_b32_e32 v82, 0xffff0000, v82
	v_and_b32_e32 v84, 0xffff0000, v84
	v_fmac_f32_e32 v88, v72, v76
	v_fmac_f32_e32 v90, v64, v68
	v_lshlrev_b32_e32 v89, 16, v83
	v_lshlrev_b32_e32 v91, 16, v85
	v_fmac_f32_e32 v82, v73, v77
	v_fmac_f32_e32 v84, v65, v69
	v_mul_f32_e32 v68, v88, v88
	v_mul_f32_e32 v69, v90, v90
	v_and_b32_e32 v83, 0xffff0000, v83
	v_and_b32_e32 v85, 0xffff0000, v85
	v_fmac_f32_e32 v89, v74, v78
	v_fmac_f32_e32 v91, v66, v70
	v_fmac_f32_e32 v68, v82, v82
	v_fmac_f32_e32 v69, v84, v84
	v_fmac_f32_e32 v83, v75, v79
	v_fmac_f32_e32 v85, v67, v71
	v_fmac_f32_e32 v68, v89, v89
	v_fmac_f32_e32 v69, v91, v91
	v_cvt_pk_bf16_f32 v64, v88, v82
	v_fmac_f32_e32 v68, v83, v83
	v_fmac_f32_e32 v69, v85, v85
	v_cvt_pk_bf16_f32 v65, v89, v83
	v_cvt_pk_bf16_f32 v66, v90, v84
	v_cvt_pk_bf16_f32 v67, v91, v85
	global_store_dwordx4 v[86:87], v[64:67], off
	s_nop 1
	v_add_f32_e32 v64, v68, v69
	v_mov_b32_e32 v65, v64
	s_nop 1
	v_permlane16_swap_b32_e32 v64, v65
	v_add_f32_e32 v64, v64, v65
	v_mov_b32_e32 v65, v64
	s_nop 1
	v_permlane32_swap_b32_e32 v64, v65
	s_and_saveexec_b64 s[38:39], s[4:5]
	s_cbranch_execz .LBB0_1238
	v_add_f32_e32 v66, v64, v65
	v_lshl_add_u64 v[64:65], v[80:81], 2, s[14:15]
	v_mov_b32_e32 v173, v66
.LBB0_1238:
	s_or_b64 exec, exec, s[38:39]
	v_add_u32_e32 v64, 0x80, v146
	v_ashrrev_i32_e32 v65, 31, v64
	v_lshlrev_b64 v[66:67], 11, v[64:65]
	v_lshl_add_u64 v[66:67], s[12:13], 0, v[66:67]
	v_lshl_add_u64 v[70:71], v[144:145], 1, v[66:67]
	s_nop 0
	v_mul_f32_e32 v60, 0xbfb8aa3b, v60
	v_mul_f32_e32 v52, 0xbfb8aa3b, v52
	v_mul_f32_e32 v61, 0xbfb8aa3b, v61
	v_mul_f32_e32 v53, 0xbfb8aa3b, v53
	v_exp_f32_e32 v60, v60
	v_exp_f32_e32 v52, v52
	v_mul_f32_e32 v62, 0xbfb8aa3b, v62
	v_mul_f32_e32 v54, 0xbfb8aa3b, v54
	v_exp_f32_e32 v61, v61
	v_exp_f32_e32 v53, v53
	v_mul_f32_e32 v63, 0xbfb8aa3b, v63
	v_mul_f32_e32 v55, 0xbfb8aa3b, v55
	v_exp_f32_e32 v62, v62
	v_exp_f32_e32 v54, v54
	v_exp_f32_e32 v63, v63
	v_exp_f32_e32 v55, v55
	v_add_f32_e32 v60, 1.0, v60
	v_add_f32_e32 v52, 1.0, v52
	v_add_f32_e32 v61, 1.0, v61
	v_add_f32_e32 v53, 1.0, v53
	v_rcp_f32_e32 v60, v60
	v_rcp_f32_e32 v52, v52
	v_add_f32_e32 v62, 1.0, v62
	v_add_f32_e32 v54, 1.0, v54
	v_rcp_f32_e32 v61, v61
	v_rcp_f32_e32 v53, v53
	v_add_f32_e32 v63, 1.0, v63
	v_add_f32_e32 v55, 1.0, v55
	v_rcp_f32_e32 v62, v62
	v_rcp_f32_e32 v54, v54
	v_rcp_f32_e32 v63, v63
	v_rcp_f32_e32 v55, v55
	s_waitcnt vmcnt(3)
	v_mov_b64_e32 v[66:67], v[196:197]
	v_mov_b64_e32 v[68:69], v[198:199]
	v_lshlrev_b32_e32 v72, 16, v66
	v_lshlrev_b32_e32 v74, 16, v68
	v_and_b32_e32 v66, 0xffff0000, v66
	v_and_b32_e32 v68, 0xffff0000, v68
	v_fmac_f32_e32 v72, v56, v60
	v_fmac_f32_e32 v74, v48, v52
	v_lshlrev_b32_e32 v73, 16, v67
	v_lshlrev_b32_e32 v75, 16, v69
	v_fmac_f32_e32 v66, v57, v61
	v_fmac_f32_e32 v68, v49, v53
	v_mul_f32_e32 v52, v72, v72
	v_mul_f32_e32 v53, v74, v74
	v_and_b32_e32 v67, 0xffff0000, v67
	v_and_b32_e32 v69, 0xffff0000, v69
	v_fmac_f32_e32 v73, v58, v62
	v_fmac_f32_e32 v75, v50, v54
	v_fmac_f32_e32 v52, v66, v66
	v_fmac_f32_e32 v53, v68, v68
	v_fmac_f32_e32 v67, v59, v63
	v_fmac_f32_e32 v69, v51, v55
	v_fmac_f32_e32 v52, v73, v73
	v_fmac_f32_e32 v53, v75, v75
	v_cvt_pk_bf16_f32 v48, v72, v66
	v_fmac_f32_e32 v52, v67, v67
	v_fmac_f32_e32 v53, v69, v69
	v_cvt_pk_bf16_f32 v49, v73, v67
	v_cvt_pk_bf16_f32 v50, v74, v68
	v_cvt_pk_bf16_f32 v51, v75, v69
	global_store_dwordx4 v[70:71], v[48:51], off
	s_nop 1
	v_add_f32_e32 v48, v52, v53
	v_mov_b32_e32 v49, v48
	s_nop 1
	v_permlane16_swap_b32_e32 v48, v49
	v_add_f32_e32 v48, v48, v49
	v_mov_b32_e32 v49, v48
	s_nop 1
	v_permlane32_swap_b32_e32 v48, v49
	s_and_saveexec_b64 s[38:39], s[4:5]
	s_cbranch_execz .LBB0_1240
	v_add_f32_e32 v50, v48, v49
	v_lshl_add_u64 v[48:49], v[64:65], 2, s[14:15]
	v_mov_b32_e32 v174, v50
.LBB0_1240:
	s_or_b64 exec, exec, s[38:39]
	v_add_u32_e32 v48, 0x90, v146
	v_ashrrev_i32_e32 v49, 31, v48
	v_lshlrev_b64 v[50:51], 11, v[48:49]
	v_lshl_add_u64 v[50:51], s[12:13], 0, v[50:51]
	v_lshl_add_u64 v[54:55], v[144:145], 1, v[50:51]
	s_nop 0
	v_mul_f32_e32 v44, 0xbfb8aa3b, v44
	v_mul_f32_e32 v36, 0xbfb8aa3b, v36
	v_mul_f32_e32 v45, 0xbfb8aa3b, v45
	v_mul_f32_e32 v37, 0xbfb8aa3b, v37
	v_exp_f32_e32 v44, v44
	v_exp_f32_e32 v36, v36
	v_mul_f32_e32 v46, 0xbfb8aa3b, v46
	v_mul_f32_e32 v38, 0xbfb8aa3b, v38
	v_exp_f32_e32 v45, v45
	v_exp_f32_e32 v37, v37
	v_mul_f32_e32 v47, 0xbfb8aa3b, v47
	v_mul_f32_e32 v39, 0xbfb8aa3b, v39
	v_exp_f32_e32 v46, v46
	v_exp_f32_e32 v38, v38
	v_exp_f32_e32 v47, v47
	v_exp_f32_e32 v39, v39
	v_add_f32_e32 v44, 1.0, v44
	v_add_f32_e32 v36, 1.0, v36
	v_add_f32_e32 v45, 1.0, v45
	v_add_f32_e32 v37, 1.0, v37
	v_rcp_f32_e32 v44, v44
	v_rcp_f32_e32 v36, v36
	v_add_f32_e32 v46, 1.0, v46
	v_add_f32_e32 v38, 1.0, v38
	v_rcp_f32_e32 v45, v45
	v_rcp_f32_e32 v37, v37
	v_add_f32_e32 v47, 1.0, v47
	v_add_f32_e32 v39, 1.0, v39
	v_rcp_f32_e32 v46, v46
	v_rcp_f32_e32 v38, v38
	v_rcp_f32_e32 v47, v47
	v_rcp_f32_e32 v39, v39
	s_waitcnt vmcnt(2)
	v_mov_b64_e32 v[50:51], v[200:201]
	v_mov_b64_e32 v[52:53], v[202:203]
	v_lshlrev_b32_e32 v56, 16, v50
	v_lshlrev_b32_e32 v58, 16, v52
	v_and_b32_e32 v50, 0xffff0000, v50
	v_and_b32_e32 v52, 0xffff0000, v52
	v_fmac_f32_e32 v56, v40, v44
	v_fmac_f32_e32 v58, v32, v36
	v_lshlrev_b32_e32 v57, 16, v51
	v_lshlrev_b32_e32 v59, 16, v53
	v_fmac_f32_e32 v50, v41, v45
	v_fmac_f32_e32 v52, v33, v37
	v_mul_f32_e32 v36, v56, v56
	v_mul_f32_e32 v37, v58, v58
	v_and_b32_e32 v51, 0xffff0000, v51
	v_and_b32_e32 v53, 0xffff0000, v53
	v_fmac_f32_e32 v57, v42, v46
	v_fmac_f32_e32 v59, v34, v38
	v_fmac_f32_e32 v36, v50, v50
	v_fmac_f32_e32 v37, v52, v52
	v_fmac_f32_e32 v51, v43, v47
	v_fmac_f32_e32 v53, v35, v39
	v_fmac_f32_e32 v36, v57, v57
	v_fmac_f32_e32 v37, v59, v59
	v_cvt_pk_bf16_f32 v32, v56, v50
	v_fmac_f32_e32 v36, v51, v51
	v_fmac_f32_e32 v37, v53, v53
	v_cvt_pk_bf16_f32 v33, v57, v51
	v_cvt_pk_bf16_f32 v34, v58, v52
	v_cvt_pk_bf16_f32 v35, v59, v53
	global_store_dwordx4 v[54:55], v[32:35], off
	s_nop 1
	v_add_f32_e32 v32, v36, v37
	v_mov_b32_e32 v33, v32
	s_nop 1
	v_permlane16_swap_b32_e32 v32, v33
	v_add_f32_e32 v32, v32, v33
	v_mov_b32_e32 v33, v32
	s_nop 1
	v_permlane32_swap_b32_e32 v32, v33
	s_and_saveexec_b64 s[38:39], s[4:5]
	s_cbranch_execz .LBB0_1242
	v_add_f32_e32 v34, v32, v33
	v_lshl_add_u64 v[32:33], v[48:49], 2, s[14:15]
	v_mov_b32_e32 v175, v34
.LBB0_1242:
	s_or_b64 exec, exec, s[38:39]
	v_add_u32_e32 v32, 0xa0, v146
	v_ashrrev_i32_e32 v33, 31, v32
	v_lshlrev_b64 v[34:35], 11, v[32:33]
	v_lshl_add_u64 v[34:35], s[12:13], 0, v[34:35]
	v_lshl_add_u64 v[38:39], v[144:145], 1, v[34:35]
	s_nop 0
	v_mul_f32_e32 v28, 0xbfb8aa3b, v28
	v_mul_f32_e32 v20, 0xbfb8aa3b, v20
	v_mul_f32_e32 v29, 0xbfb8aa3b, v29
	v_mul_f32_e32 v21, 0xbfb8aa3b, v21
	v_exp_f32_e32 v28, v28
	v_exp_f32_e32 v20, v20
	v_mul_f32_e32 v30, 0xbfb8aa3b, v30
	v_mul_f32_e32 v22, 0xbfb8aa3b, v22
	v_exp_f32_e32 v29, v29
	v_exp_f32_e32 v21, v21
	v_mul_f32_e32 v31, 0xbfb8aa3b, v31
	v_mul_f32_e32 v23, 0xbfb8aa3b, v23
	v_exp_f32_e32 v30, v30
	v_exp_f32_e32 v22, v22
	v_exp_f32_e32 v31, v31
	v_exp_f32_e32 v23, v23
	v_add_f32_e32 v28, 1.0, v28
	v_add_f32_e32 v20, 1.0, v20
	v_add_f32_e32 v29, 1.0, v29
	v_add_f32_e32 v21, 1.0, v21
	v_rcp_f32_e32 v28, v28
	v_rcp_f32_e32 v20, v20
	v_add_f32_e32 v30, 1.0, v30
	v_add_f32_e32 v22, 1.0, v22
	v_rcp_f32_e32 v29, v29
	v_rcp_f32_e32 v21, v21
	v_add_f32_e32 v31, 1.0, v31
	v_add_f32_e32 v23, 1.0, v23
	v_rcp_f32_e32 v30, v30
	v_rcp_f32_e32 v22, v22
	v_rcp_f32_e32 v31, v31
	v_rcp_f32_e32 v23, v23
	s_waitcnt vmcnt(1)
	v_mov_b64_e32 v[34:35], v[204:205]
	v_mov_b64_e32 v[36:37], v[206:207]
	v_lshlrev_b32_e32 v40, 16, v34
	v_lshlrev_b32_e32 v42, 16, v36
	v_and_b32_e32 v34, 0xffff0000, v34
	v_and_b32_e32 v36, 0xffff0000, v36
	v_fmac_f32_e32 v40, v24, v28
	v_fmac_f32_e32 v42, v16, v20
	v_lshlrev_b32_e32 v41, 16, v35
	v_lshlrev_b32_e32 v43, 16, v37
	v_fmac_f32_e32 v34, v25, v29
	v_fmac_f32_e32 v36, v17, v21
	v_mul_f32_e32 v20, v40, v40
	v_mul_f32_e32 v21, v42, v42
	v_and_b32_e32 v35, 0xffff0000, v35
	v_and_b32_e32 v37, 0xffff0000, v37
	v_fmac_f32_e32 v41, v26, v30
	v_fmac_f32_e32 v43, v18, v22
	v_fmac_f32_e32 v20, v34, v34
	v_fmac_f32_e32 v21, v36, v36
	v_fmac_f32_e32 v35, v27, v31
	v_fmac_f32_e32 v37, v19, v23
	v_fmac_f32_e32 v20, v41, v41
	v_fmac_f32_e32 v21, v43, v43
	v_cvt_pk_bf16_f32 v16, v40, v34
	v_fmac_f32_e32 v20, v35, v35
	v_fmac_f32_e32 v21, v37, v37
	v_cvt_pk_bf16_f32 v17, v41, v35
	v_cvt_pk_bf16_f32 v18, v42, v36
	v_cvt_pk_bf16_f32 v19, v43, v37
	global_store_dwordx4 v[38:39], v[16:19], off
	s_nop 1
	v_add_f32_e32 v16, v20, v21
	v_mov_b32_e32 v17, v16
	s_nop 1
	v_permlane16_swap_b32_e32 v16, v17
	v_add_f32_e32 v16, v16, v17
	v_mov_b32_e32 v17, v16
	s_nop 1
	v_permlane32_swap_b32_e32 v16, v17
	s_and_saveexec_b64 s[38:39], s[4:5]
	s_cbranch_execz .LBB0_1244
	v_add_f32_e32 v18, v16, v17
	v_lshl_add_u64 v[16:17], v[32:33], 2, s[14:15]
	v_mov_b32_e32 v176, v18
.LBB0_1244:
	s_or_b64 exec, exec, s[38:39]
	v_add_u32_e32 v16, 0xb0, v146
	v_ashrrev_i32_e32 v17, 31, v16
	v_lshlrev_b64 v[18:19], 11, v[16:17]
	v_lshl_add_u64 v[18:19], s[12:13], 0, v[18:19]
	v_lshl_add_u64 v[22:23], v[144:145], 1, v[18:19]
	s_nop 0
	v_mul_f32_e32 v12, 0xbfb8aa3b, v12
	v_mul_f32_e32 v4, 0xbfb8aa3b, v4
	v_mul_f32_e32 v13, 0xbfb8aa3b, v13
	v_mul_f32_e32 v5, 0xbfb8aa3b, v5
	v_exp_f32_e32 v12, v12
	v_exp_f32_e32 v4, v4
	v_mul_f32_e32 v14, 0xbfb8aa3b, v14
	v_mul_f32_e32 v6, 0xbfb8aa3b, v6
	v_exp_f32_e32 v13, v13
	v_exp_f32_e32 v5, v5
	v_mul_f32_e32 v15, 0xbfb8aa3b, v15
	v_mul_f32_e32 v7, 0xbfb8aa3b, v7
	v_exp_f32_e32 v14, v14
	v_exp_f32_e32 v6, v6
	v_exp_f32_e32 v15, v15
	v_exp_f32_e32 v7, v7
	v_add_f32_e32 v12, 1.0, v12
	v_add_f32_e32 v4, 1.0, v4
	v_add_f32_e32 v13, 1.0, v13
	v_add_f32_e32 v5, 1.0, v5
	v_rcp_f32_e32 v12, v12
	v_rcp_f32_e32 v4, v4
	v_add_f32_e32 v14, 1.0, v14
	v_add_f32_e32 v6, 1.0, v6
	v_rcp_f32_e32 v13, v13
	v_rcp_f32_e32 v5, v5
	v_add_f32_e32 v15, 1.0, v15
	v_add_f32_e32 v7, 1.0, v7
	v_rcp_f32_e32 v14, v14
	v_rcp_f32_e32 v6, v6
	v_rcp_f32_e32 v15, v15
	v_rcp_f32_e32 v7, v7
	s_waitcnt vmcnt(0)
	v_mov_b64_e32 v[18:19], v[212:213]
	v_mov_b64_e32 v[20:21], v[214:215]
	v_lshlrev_b32_e32 v24, 16, v18
	v_lshlrev_b32_e32 v26, 16, v20
	v_and_b32_e32 v18, 0xffff0000, v18
	v_and_b32_e32 v20, 0xffff0000, v20
	v_fmac_f32_e32 v24, v8, v12
	v_fmac_f32_e32 v26, v0, v4
	v_lshlrev_b32_e32 v25, 16, v19
	v_lshlrev_b32_e32 v27, 16, v21
	v_fmac_f32_e32 v18, v9, v13
	v_fmac_f32_e32 v20, v1, v5
	v_mul_f32_e32 v4, v24, v24
	v_mul_f32_e32 v5, v26, v26
	v_and_b32_e32 v19, 0xffff0000, v19
	v_and_b32_e32 v21, 0xffff0000, v21
	v_fmac_f32_e32 v25, v10, v14
	v_fmac_f32_e32 v27, v2, v6
	v_fmac_f32_e32 v4, v18, v18
	v_fmac_f32_e32 v5, v20, v20
	v_fmac_f32_e32 v19, v11, v15
	v_fmac_f32_e32 v21, v3, v7
	v_fmac_f32_e32 v4, v25, v25
	v_fmac_f32_e32 v5, v27, v27
	v_cvt_pk_bf16_f32 v0, v24, v18
	v_fmac_f32_e32 v4, v19, v19
	v_fmac_f32_e32 v5, v21, v21
	v_cvt_pk_bf16_f32 v1, v25, v19
	v_cvt_pk_bf16_f32 v2, v26, v20
	v_cvt_pk_bf16_f32 v3, v27, v21
	global_store_dwordx4 v[22:23], v[0:3], off
	s_nop 1
	v_add_f32_e32 v0, v4, v5
	v_mov_b32_e32 v1, v0
	s_nop 1
	v_permlane16_swap_b32_e32 v0, v1
	v_add_f32_e32 v0, v0, v1
	v_mov_b32_e32 v1, v0
	s_nop 1
	v_permlane32_swap_b32_e32 v0, v1
	s_and_saveexec_b64 s[38:39], s[4:5]
	s_cbranch_execz .LBB0_1246
	v_add_f32_e32 v2, v0, v1
	v_lshl_add_u64 v[0:1], v[16:17], 2, s[14:15]
	global_atomic_add_f32 v[168:169], v170, off
	global_atomic_add_f32 v[168:169], v171, off offset:64
	global_atomic_add_f32 v[168:169], v172, off offset:128
	global_atomic_add_f32 v[168:169], v173, off offset:192
	global_atomic_add_f32 v[168:169], v174, off offset:512
	global_atomic_add_f32 v[168:169], v175, off offset:576
	global_atomic_add_f32 v[168:169], v176, off offset:640
	global_atomic_add_f32 v[0:1], v2, off
